# GEMM K-loops: the redundant s_setprio 0 / s_setprio 1 pair between the two 16-MFMA groups of each block removed (20 sites); on top of eb6
# speedup vs baseline: 1.0022x; 1.0022x over previous
.LBB0_245:
	s_waitcnt lgkmcnt(0)
	s_barrier
	s_setprio 1
	s_waitcnt lgkmcnt(0)
	v_mfma_f32_16x16x32_bf16 v[82:85], v[166:169], v[190:193], v[82:85]
	v_mfma_f32_16x16x32_bf16 v[78:81], v[174:177], v[190:193], v[78:81]
	v_mfma_f32_16x16x32_bf16 v[50:53], v[166:169], v[182:185], v[50:53]
	v_mfma_f32_16x16x32_bf16 v[46:49], v[174:177], v[182:185], v[46:49]
	v_mfma_f32_16x16x32_bf16 v[34:37], v[166:169], v[62:65], v[34:37]
	v_mfma_f32_16x16x32_bf16 v[30:33], v[174:177], v[62:65], v[30:33]
	v_mfma_f32_16x16x32_bf16 v[18:21], v[166:169], v[54:57], v[18:21]
	v_mfma_f32_16x16x32_bf16 v[10:13], v[174:177], v[54:57], v[10:13]
	v_mfma_f32_16x16x32_bf16 v[82:85], v[170:173], v[194:197], v[82:85]
	v_mfma_f32_16x16x32_bf16 v[78:81], v[178:181], v[194:197], v[78:81]
	v_mfma_f32_16x16x32_bf16 v[50:53], v[170:173], v[186:189], v[50:53]
	v_mfma_f32_16x16x32_bf16 v[46:49], v[178:181], v[186:189], v[46:49]
	v_mfma_f32_16x16x32_bf16 v[34:37], v[170:173], v[66:69], v[34:37]
	v_mfma_f32_16x16x32_bf16 v[30:33], v[178:181], v[66:69], v[30:33]
	v_mfma_f32_16x16x32_bf16 v[18:21], v[170:173], v[58:61], v[18:21]
	v_mfma_f32_16x16x32_bf16 v[10:13], v[178:181], v[58:61], v[10:13]
	v_mfma_f32_16x16x32_bf16 v[74:77], v[150:153], v[190:193], v[74:77]
	v_mfma_f32_16x16x32_bf16 v[70:73], v[158:161], v[190:193], v[70:73]
	v_mfma_f32_16x16x32_bf16 v[42:45], v[150:153], v[182:185], v[42:45]
	v_mfma_f32_16x16x32_bf16 v[38:41], v[158:161], v[182:185], v[38:41]
	v_mfma_f32_16x16x32_bf16 v[26:29], v[150:153], v[62:65], v[26:29]
	v_mfma_f32_16x16x32_bf16 v[22:25], v[158:161], v[62:65], v[22:25]
	v_mfma_f32_16x16x32_bf16 v[6:9], v[150:153], v[54:57], v[6:9]
	v_mfma_f32_16x16x32_bf16 v[2:5], v[158:161], v[54:57], v[2:5]
	v_mfma_f32_16x16x32_bf16 v[74:77], v[154:157], v[194:197], v[74:77]
	v_mfma_f32_16x16x32_bf16 v[70:73], v[162:165], v[194:197], v[70:73]
	v_mfma_f32_16x16x32_bf16 v[42:45], v[154:157], v[186:189], v[42:45]
	v_mfma_f32_16x16x32_bf16 v[38:41], v[162:165], v[186:189], v[38:41]
	v_mfma_f32_16x16x32_bf16 v[26:29], v[154:157], v[66:69], v[26:29]
	v_mfma_f32_16x16x32_bf16 v[22:25], v[162:165], v[66:69], v[22:25]
	v_mfma_f32_16x16x32_bf16 v[6:9], v[154:157], v[58:61], v[6:9]
	v_mfma_f32_16x16x32_bf16 v[2:5], v[162:165], v[58:61], v[2:5]
	s_setprio 0
	s_barrier
	s_add_i32 s65, s65, 2
	s_add_u32 s8, s8, 0x100
	s_addc_u32 s9, s9, 0
	s_add_u32 s33, s33, 0x100
	s_addc_u32 s64, s64, 0
	s_cmp_gt_u32 s65, 29
	s_cbranch_scc1 .LBB0_256
.LBB0_246:
	ds_read_b128 v[166:169], v236
	ds_read_b128 v[170:173], v236 offset:1024
	ds_read_b128 v[174:177], v236 offset:2048
	ds_read_b128 v[178:181], v236 offset:3072
	ds_read_b128 v[150:153], v237
	ds_read_b128 v[154:157], v237 offset:1024
	ds_read_b128 v[158:161], v237 offset:2048
	ds_read_b128 v[162:165], v237 offset:3072
	s_add_u32 s88, s8, 0xfff80080
	s_addc_u32 s89, s9, -1
	s_cmp_lg_u32 s65, 28
	s_cselect_b64 s[90:91], -1, 0
	s_and_b64 s[86:87], s[90:91], exec
	s_cselect_b32 s87, s64, s77
	s_cselect_b32 s86, s33, s79
	s_cselect_b32 s89, s89, s5
	s_cselect_b32 s88, s88, s7
	v_lshl_add_u64 v[54:55], s[8:9], 0, v[222:223]
	s_add_i32 m0, s29, 0xc000
	ds_read_b128 v[182:185], v245
	ds_read_b128 v[186:189], v245 offset:1024
	ds_read_b128 v[190:193], v245 offset:2048
	ds_read_b128 v[194:197], v245 offset:3072
	ds_read_b128 v[198:201], v245 offset:4096
	ds_read_b128 v[202:205], v245 offset:5120
	ds_read_b128 v[206:209], v245 offset:6144
	ds_read_b128 v[210:213], v245 offset:7168
	global_load_lds_dwordx4 v[54:55], off
	v_lshl_add_u64 v[54:55], s[8:9], 0, v[224:225]
	s_add_i32 m0, s29, 0xe000
	s_nop 0
	global_load_lds_dwordx4 v[54:55], off
	s_waitcnt vmcnt(8)
	s_waitcnt lgkmcnt(0)
	s_barrier
	s_setprio 1
	s_waitcnt lgkmcnt(0)
	v_mfma_f32_16x16x32_bf16 v[54:57], v[166:169], v[182:185], v[146:149]
	v_mfma_f32_16x16x32_bf16 v[58:61], v[174:177], v[182:185], v[142:145]
	v_mfma_f32_16x16x32_bf16 v[62:65], v[166:169], v[190:193], v[130:133]
	v_mfma_f32_16x16x32_bf16 v[66:69], v[174:177], v[190:193], v[126:129]
	v_mfma_f32_16x16x32_bf16 v[114:117], v[166:169], v[198:201], v[114:117]
	v_mfma_f32_16x16x32_bf16 v[110:113], v[174:177], v[198:201], v[110:113]
	v_mfma_f32_16x16x32_bf16 v[98:101], v[166:169], v[206:209], v[98:101]
	v_mfma_f32_16x16x32_bf16 v[94:97], v[174:177], v[206:209], v[94:97]
	v_mfma_f32_16x16x32_bf16 v[54:57], v[170:173], v[186:189], v[54:57]
	v_mfma_f32_16x16x32_bf16 v[58:61], v[178:181], v[186:189], v[58:61]
	v_mfma_f32_16x16x32_bf16 v[62:65], v[170:173], v[194:197], v[62:65]
	v_mfma_f32_16x16x32_bf16 v[66:69], v[178:181], v[194:197], v[66:69]
	v_mfma_f32_16x16x32_bf16 v[114:117], v[170:173], v[202:205], v[114:117]
	v_mfma_f32_16x16x32_bf16 v[110:113], v[178:181], v[202:205], v[110:113]
	v_mfma_f32_16x16x32_bf16 v[98:101], v[170:173], v[210:213], v[98:101]
	v_mfma_f32_16x16x32_bf16 v[94:97], v[178:181], v[210:213], v[94:97]
	v_mfma_f32_16x16x32_bf16 v[126:129], v[150:153], v[182:185], v[138:141]
	v_mfma_f32_16x16x32_bf16 v[138:141], v[154:157], v[186:189], v[126:129]
	v_mfma_f32_16x16x32_bf16 v[126:129], v[158:161], v[182:185], v[134:137]
	v_mfma_f32_16x16x32_bf16 v[122:125], v[150:153], v[190:193], v[122:125]
	v_mfma_f32_16x16x32_bf16 v[118:121], v[158:161], v[190:193], v[118:121]
	v_mfma_f32_16x16x32_bf16 v[106:109], v[150:153], v[198:201], v[106:109]
	v_mfma_f32_16x16x32_bf16 v[102:105], v[158:161], v[198:201], v[102:105]
	v_mfma_f32_16x16x32_bf16 v[90:93], v[150:153], v[206:209], v[90:93]
	v_mfma_f32_16x16x32_bf16 v[86:89], v[158:161], v[206:209], v[86:89]
	v_mfma_f32_16x16x32_bf16 v[134:137], v[162:165], v[186:189], v[126:129]
	v_mfma_f32_16x16x32_bf16 v[122:125], v[154:157], v[194:197], v[122:125]
	v_mfma_f32_16x16x32_bf16 v[118:121], v[162:165], v[194:197], v[118:121]
	v_mfma_f32_16x16x32_bf16 v[106:109], v[154:157], v[202:205], v[106:109]
	v_mfma_f32_16x16x32_bf16 v[102:105], v[162:165], v[202:205], v[102:105]
	v_mfma_f32_16x16x32_bf16 v[90:93], v[154:157], v[210:213], v[90:93]
	v_mfma_f32_16x16x32_bf16 v[86:89], v[162:165], v[210:213], v[86:89]
	s_setprio 0
	s_barrier
	ds_read_b128 v[190:193], v245 offset:16384
	ds_read_b128 v[194:197], v245 offset:17408
	ds_read_b128 v[182:185], v245 offset:18432
	ds_read_b128 v[186:189], v245 offset:19456
	ds_read_b128 v[142:145], v245 offset:20480
	ds_read_b128 v[146:149], v245 offset:21504
	ds_read_b128 v[126:129], v245 offset:22528
	ds_read_b128 v[130:133], v245 offset:23552
	s_or_b64 s[90:91], s[80:81], s[90:91]
	s_xor_b64 s[92:93], s[90:91], -1
	s_mov_b64 s[94:95], -1
	s_and_b64 vcc, exec, s[92:93]
	s_cbranch_vccz .LBB0_248
	s_waitcnt vmcnt(2)
	s_mov_b64 s[94:95], 0

.LBB0_250:
	s_waitcnt lgkmcnt(0)
	s_barrier
	s_setprio 1
	s_waitcnt lgkmcnt(0)
	v_mfma_f32_16x16x32_bf16 v[82:85], v[166:169], v[190:193], v[82:85]
	v_mfma_f32_16x16x32_bf16 v[78:81], v[174:177], v[190:193], v[78:81]
	v_mfma_f32_16x16x32_bf16 v[50:53], v[166:169], v[182:185], v[50:53]
	v_mfma_f32_16x16x32_bf16 v[46:49], v[174:177], v[182:185], v[46:49]
	v_mfma_f32_16x16x32_bf16 v[34:37], v[166:169], v[142:145], v[34:37]
	v_mfma_f32_16x16x32_bf16 v[30:33], v[174:177], v[142:145], v[30:33]
	v_mfma_f32_16x16x32_bf16 v[18:21], v[166:169], v[126:129], v[18:21]
	v_mfma_f32_16x16x32_bf16 v[10:13], v[174:177], v[126:129], v[10:13]
	v_mfma_f32_16x16x32_bf16 v[82:85], v[170:173], v[194:197], v[82:85]
	v_mfma_f32_16x16x32_bf16 v[78:81], v[178:181], v[194:197], v[78:81]
	v_mfma_f32_16x16x32_bf16 v[50:53], v[170:173], v[186:189], v[50:53]
	v_mfma_f32_16x16x32_bf16 v[46:49], v[178:181], v[186:189], v[46:49]
	v_mfma_f32_16x16x32_bf16 v[34:37], v[170:173], v[146:149], v[34:37]
	v_mfma_f32_16x16x32_bf16 v[30:33], v[178:181], v[146:149], v[30:33]
	v_mfma_f32_16x16x32_bf16 v[18:21], v[170:173], v[130:133], v[18:21]
	v_mfma_f32_16x16x32_bf16 v[10:13], v[178:181], v[130:133], v[10:13]
	v_mfma_f32_16x16x32_bf16 v[74:77], v[150:153], v[190:193], v[74:77]
	v_mfma_f32_16x16x32_bf16 v[70:73], v[158:161], v[190:193], v[70:73]
	v_mfma_f32_16x16x32_bf16 v[42:45], v[150:153], v[182:185], v[42:45]
	v_mfma_f32_16x16x32_bf16 v[38:41], v[158:161], v[182:185], v[38:41]
	v_mfma_f32_16x16x32_bf16 v[26:29], v[150:153], v[142:145], v[26:29]
	v_mfma_f32_16x16x32_bf16 v[22:25], v[158:161], v[142:145], v[22:25]
	v_mfma_f32_16x16x32_bf16 v[6:9], v[150:153], v[126:129], v[6:9]
	v_mfma_f32_16x16x32_bf16 v[2:5], v[158:161], v[126:129], v[2:5]
	v_mfma_f32_16x16x32_bf16 v[74:77], v[154:157], v[194:197], v[74:77]
	v_mfma_f32_16x16x32_bf16 v[70:73], v[162:165], v[194:197], v[70:73]
	v_mfma_f32_16x16x32_bf16 v[42:45], v[154:157], v[186:189], v[42:45]
	v_mfma_f32_16x16x32_bf16 v[38:41], v[162:165], v[186:189], v[38:41]
	v_mfma_f32_16x16x32_bf16 v[26:29], v[154:157], v[146:149], v[26:29]
	v_mfma_f32_16x16x32_bf16 v[22:25], v[162:165], v[146:149], v[22:25]
	v_mfma_f32_16x16x32_bf16 v[6:9], v[154:157], v[130:133], v[6:9]
	v_mfma_f32_16x16x32_bf16 v[2:5], v[162:165], v[130:133], v[2:5]
	s_setprio 0
	s_barrier
	v_add_u32_e32 v0, 0x18000, v235
	ds_read_b128 v[166:169], v0
	ds_read_b128 v[170:173], v0 offset:1024
	ds_read_b128 v[174:177], v0 offset:2048
	ds_read_b128 v[178:181], v0 offset:3072
	v_add_u32_e32 v0, 0x1c000, v235
	ds_read_b128 v[150:153], v0
	ds_read_b128 v[154:157], v0 offset:1024
	ds_read_b128 v[158:161], v0 offset:2048
	ds_read_b128 v[162:165], v0 offset:3072
	ds_read_b128 v[206:209], v245 offset:32768
	ds_read_b128 v[210:213], v245 offset:33792
	ds_read_b128 v[198:201], v245 offset:34816
	ds_read_b128 v[202:205], v245 offset:35840
	ds_read_b128 v[190:193], v245 offset:36864
	ds_read_b128 v[194:197], v245 offset:37888
	ds_read_b128 v[182:185], v245 offset:38912
	ds_read_b128 v[186:189], v245 offset:39936
	s_mov_b64 s[94:95], -1
	s_and_b64 vcc, exec, s[92:93]
	s_cbranch_vccz .LBB0_252
	s_waitcnt vmcnt(0)
	s_mov_b64 s[94:95], 0

.LBB0_254:
	s_waitcnt lgkmcnt(0)
	s_barrier
	s_setprio 1
	s_waitcnt lgkmcnt(0)
	v_mfma_f32_16x16x32_bf16 v[54:57], v[166:169], v[206:209], v[54:57]
	v_mfma_f32_16x16x32_bf16 v[146:149], v[170:173], v[210:213], v[54:57]
	v_mfma_f32_16x16x32_bf16 v[54:57], v[174:177], v[206:209], v[58:61]
	v_mfma_f32_16x16x32_bf16 v[142:145], v[178:181], v[210:213], v[54:57]
	v_mfma_f32_16x16x32_bf16 v[54:57], v[166:169], v[198:201], v[62:65]
	v_mfma_f32_16x16x32_bf16 v[130:133], v[170:173], v[202:205], v[54:57]
	v_mfma_f32_16x16x32_bf16 v[54:57], v[174:177], v[198:201], v[66:69]
	v_mfma_f32_16x16x32_bf16 v[126:129], v[178:181], v[202:205], v[54:57]
	v_mfma_f32_16x16x32_bf16 v[54:57], v[166:169], v[190:193], v[114:117]
	v_mfma_f32_16x16x32_bf16 v[114:117], v[170:173], v[194:197], v[54:57]
	v_mfma_f32_16x16x32_bf16 v[54:57], v[174:177], v[190:193], v[110:113]
	v_mfma_f32_16x16x32_bf16 v[110:113], v[178:181], v[194:197], v[54:57]
	v_mfma_f32_16x16x32_bf16 v[54:57], v[166:169], v[182:185], v[98:101]
	v_mfma_f32_16x16x32_bf16 v[98:101], v[170:173], v[186:189], v[54:57]
	v_mfma_f32_16x16x32_bf16 v[54:57], v[174:177], v[182:185], v[94:97]
	v_mfma_f32_16x16x32_bf16 v[94:97], v[178:181], v[186:189], v[54:57]
	v_mfma_f32_16x16x32_bf16 v[54:57], v[150:153], v[206:209], v[138:141]
	v_mfma_f32_16x16x32_bf16 v[138:141], v[154:157], v[210:213], v[54:57]
	v_mfma_f32_16x16x32_bf16 v[54:57], v[158:161], v[206:209], v[134:137]
	v_mfma_f32_16x16x32_bf16 v[134:137], v[162:165], v[210:213], v[54:57]
	v_mfma_f32_16x16x32_bf16 v[54:57], v[150:153], v[198:201], v[122:125]
	v_mfma_f32_16x16x32_bf16 v[122:125], v[154:157], v[202:205], v[54:57]
	v_mfma_f32_16x16x32_bf16 v[54:57], v[158:161], v[198:201], v[118:121]
	v_mfma_f32_16x16x32_bf16 v[118:121], v[162:165], v[202:205], v[54:57]
	v_mfma_f32_16x16x32_bf16 v[54:57], v[150:153], v[190:193], v[106:109]
	v_mfma_f32_16x16x32_bf16 v[106:109], v[154:157], v[194:197], v[54:57]
	v_mfma_f32_16x16x32_bf16 v[54:57], v[158:161], v[190:193], v[102:105]
	v_mfma_f32_16x16x32_bf16 v[102:105], v[162:165], v[194:197], v[54:57]
	v_mfma_f32_16x16x32_bf16 v[54:57], v[150:153], v[182:185], v[90:93]
	v_mfma_f32_16x16x32_bf16 v[90:93], v[154:157], v[186:189], v[54:57]
	v_mfma_f32_16x16x32_bf16 v[54:57], v[158:161], v[182:185], v[86:89]
	v_mfma_f32_16x16x32_bf16 v[86:89], v[162:165], v[186:189], v[54:57]
	s_setprio 0
	s_barrier
	ds_read_b128 v[190:193], v245 offset:49152
	ds_read_b128 v[194:197], v245 offset:50176
	ds_read_b128 v[182:185], v245 offset:51200
	ds_read_b128 v[186:189], v245 offset:52224
	ds_read_b128 v[62:65], v245 offset:53248
	ds_read_b128 v[66:69], v245 offset:54272
	ds_read_b128 v[54:57], v245 offset:55296
	ds_read_b128 v[58:61], v245 offset:56320
	s_andn2_b64 vcc, exec, s[90:91]
	s_cbranch_vccnz .LBB0_245
	s_mov_b32 m0, s1
	v_lshl_add_u64 v[198:199], v[232:233], 0, s[16:17]
	s_add_u32 s86, s86, 0x80080
	global_load_lds_dwordx4 v[198:199], off
	v_lshl_add_u64 v[198:199], v[230:231], 0, s[16:17]
	s_mov_b32 m0, s38
	s_addc_u32 s87, s87, 0
	global_load_lds_dwordx4 v[198:199], off
	v_lshl_add_u64 v[198:199], s[86:87], 0, v[216:217]
	s_mov_b32 m0, s46
	s_nop 0
	global_load_lds_dwordx4 v[198:199], off
	v_lshl_add_u64 v[198:199], s[86:87], 0, v[220:221]
	s_mov_b32 m0, s47
	s_nop 0
	global_load_lds_dwordx4 v[198:199], off
	v_lshl_add_u64 v[198:199], v[228:229], 0, s[16:17]
	s_mov_b32 m0, s40
	s_nop 0
	global_load_lds_dwordx4 v[198:199], off
	v_lshl_add_u64 v[198:199], v[226:227], 0, s[16:17]
	s_mov_b32 m0, s41
	s_nop 0
	global_load_lds_dwordx4 v[198:199], off
	s_waitcnt vmcnt(8)
	s_branch .LBB0_245

.LBB0_1310:
	s_waitcnt lgkmcnt(0)
	s_barrier
	s_setprio 1
	s_waitcnt lgkmcnt(0)
	v_mfma_f32_16x16x32_bf16 v[78:81], v[150:153], v[190:193], v[78:81]
	v_mfma_f32_16x16x32_bf16 v[86:89], v[158:161], v[190:193], v[86:89]
	v_mfma_f32_16x16x32_bf16 v[110:113], v[150:153], v[182:185], v[110:113]
	v_mfma_f32_16x16x32_bf16 v[114:117], v[158:161], v[182:185], v[114:117]
	v_mfma_f32_16x16x32_bf16 v[130:133], v[150:153], v[174:177], v[130:133]
	v_mfma_f32_16x16x32_bf16 v[118:121], v[158:161], v[174:177], v[118:121]
	v_mfma_f32_16x16x32_bf16 v[90:93], v[150:153], v[166:169], v[90:93]
	v_mfma_f32_16x16x32_bf16 v[82:85], v[158:161], v[166:169], v[82:85]
	v_mfma_f32_16x16x32_bf16 v[78:81], v[154:157], v[194:197], v[78:81]
	v_mfma_f32_16x16x32_bf16 v[86:89], v[162:165], v[194:197], v[86:89]
	v_mfma_f32_16x16x32_bf16 v[110:113], v[154:157], v[186:189], v[110:113]
	v_mfma_f32_16x16x32_bf16 v[114:117], v[162:165], v[186:189], v[114:117]
	v_mfma_f32_16x16x32_bf16 v[130:133], v[154:157], v[178:181], v[130:133]
	v_mfma_f32_16x16x32_bf16 v[118:121], v[162:165], v[178:181], v[118:121]
	v_mfma_f32_16x16x32_bf16 v[90:93], v[154:157], v[170:173], v[90:93]
	v_mfma_f32_16x16x32_bf16 v[82:85], v[162:165], v[170:173], v[82:85]
	v_mfma_f32_16x16x32_bf16 v[94:97], v[134:137], v[190:193], v[94:97]
	v_mfma_f32_16x16x32_bf16 v[98:101], v[142:145], v[190:193], v[98:101]
	v_mfma_f32_16x16x32_bf16 v[122:125], v[134:137], v[182:185], v[122:125]
	v_mfma_f32_16x16x32_bf16 v[126:129], v[142:145], v[182:185], v[126:129]
	v_mfma_f32_16x16x32_bf16 v[106:109], v[134:137], v[174:177], v[106:109]
	v_mfma_f32_16x16x32_bf16 v[102:105], v[142:145], v[174:177], v[102:105]
	v_mfma_f32_16x16x32_bf16 v[66:69], v[134:137], v[166:169], v[66:69]
	v_mfma_f32_16x16x32_bf16 v[62:65], v[142:145], v[166:169], v[62:65]
	v_mfma_f32_16x16x32_bf16 v[94:97], v[138:141], v[194:197], v[94:97]
	v_mfma_f32_16x16x32_bf16 v[98:101], v[146:149], v[194:197], v[98:101]
	v_mfma_f32_16x16x32_bf16 v[122:125], v[138:141], v[186:189], v[122:125]
	v_mfma_f32_16x16x32_bf16 v[126:129], v[146:149], v[186:189], v[126:129]
	v_mfma_f32_16x16x32_bf16 v[106:109], v[138:141], v[178:181], v[106:109]
	v_mfma_f32_16x16x32_bf16 v[102:105], v[146:149], v[178:181], v[102:105]
	v_mfma_f32_16x16x32_bf16 v[66:69], v[138:141], v[170:173], v[66:69]
	v_mfma_f32_16x16x32_bf16 v[62:65], v[146:149], v[170:173], v[62:65]
	s_setprio 0
	s_barrier
	s_cmp_ge_u32 s60, s41
	s_cbranch_scc1 .LBB0_1321
.LBB0_1311:
	s_cmp_eq_u32 s60, s74
	s_cselect_b64 s[10:11], -1, 0
	s_or_b32 s14, s60, 1
	s_add_i32 s60, s60, 2
	s_mov_b32 s61, s15
	s_lshl_b64 s[62:63], s[60:61], 7
	v_add_u32_e32 v0, 0x10000, v235
	s_add_u32 s61, s56, s62
	ds_read_b128 v[150:153], v0
	ds_read_b128 v[154:157], v0 offset:1024
	ds_read_b128 v[158:161], v0 offset:2048
	ds_read_b128 v[162:165], v0 offset:3072
	v_add_u32_e32 v0, 0x14000, v235
	s_addc_u32 s66, s57, s63
	ds_read_b128 v[134:137], v0
	ds_read_b128 v[138:141], v0 offset:1024
	ds_read_b128 v[142:145], v0 offset:2048
	ds_read_b128 v[146:149], v0 offset:3072
	s_and_b64 s[64:65], s[10:11], exec
	s_cselect_b32 s62, 0, s62
	s_cselect_b32 s63, 0, s63
	s_add_u32 s62, s42, s62
	s_addc_u32 s63, s43, s63
	s_and_b64 s[64:65], s[10:11], exec
	s_cselect_b32 s65, s53, s66
	s_cselect_b32 s64, s52, s61
	s_lshl_b64 s[66:67], s[14:15], 7
	s_add_u32 s66, s33, s66
	s_addc_u32 s67, s84, s67
	v_lshl_add_u64 v[224:225], s[66:67], 0, v[202:203]
	s_add_i32 m0, s21, 0xc000
	ds_read_b128 v[166:169], v236
	ds_read_b128 v[170:173], v236 offset:1024
	ds_read_b128 v[174:177], v236 offset:2048
	ds_read_b128 v[178:181], v236 offset:3072
	ds_read_b128 v[182:185], v236 offset:4096
	ds_read_b128 v[186:189], v236 offset:5120
	ds_read_b128 v[190:193], v236 offset:6144
	ds_read_b128 v[194:197], v236 offset:7168
	global_load_lds_dwordx4 v[224:225], off
	v_lshl_add_u64 v[224:225], s[66:67], 0, v[198:199]
	s_add_i32 m0, s21, 0xe000
	s_nop 0
	global_load_lds_dwordx4 v[224:225], off
	s_waitcnt vmcnt(8)
	s_waitcnt lgkmcnt(0)
	s_barrier
	s_setprio 1
	s_waitcnt lgkmcnt(0)
	v_mfma_f32_16x16x32_bf16 v[30:33], v[150:153], v[166:169], v[30:33]
	v_mfma_f32_16x16x32_bf16 v[34:37], v[158:161], v[166:169], v[34:37]
	v_mfma_f32_16x16x32_bf16 v[6:9], v[150:153], v[174:177], v[6:9]
	v_mfma_f32_16x16x32_bf16 v[2:5], v[158:161], v[174:177], v[2:5]
	v_mfma_f32_16x16x32_bf16 v[22:25], v[150:153], v[182:185], v[22:25]
	v_mfma_f32_16x16x32_bf16 v[26:29], v[158:161], v[182:185], v[26:29]
	v_mfma_f32_16x16x32_bf16 v[54:57], v[150:153], v[190:193], v[54:57]
	v_mfma_f32_16x16x32_bf16 v[58:61], v[158:161], v[190:193], v[58:61]
	v_mfma_f32_16x16x32_bf16 v[30:33], v[154:157], v[170:173], v[30:33]
	v_mfma_f32_16x16x32_bf16 v[34:37], v[162:165], v[170:173], v[34:37]
	v_mfma_f32_16x16x32_bf16 v[6:9], v[154:157], v[178:181], v[6:9]
	v_mfma_f32_16x16x32_bf16 v[2:5], v[162:165], v[178:181], v[2:5]
	v_mfma_f32_16x16x32_bf16 v[22:25], v[154:157], v[186:189], v[22:25]
	v_mfma_f32_16x16x32_bf16 v[26:29], v[162:165], v[186:189], v[26:29]
	v_mfma_f32_16x16x32_bf16 v[54:57], v[154:157], v[194:197], v[54:57]
	v_mfma_f32_16x16x32_bf16 v[58:61], v[162:165], v[194:197], v[58:61]
	v_mfma_f32_16x16x32_bf16 v[46:49], v[134:137], v[166:169], v[46:49]
	v_mfma_f32_16x16x32_bf16 v[50:53], v[142:145], v[166:169], v[50:53]
	v_mfma_f32_16x16x32_bf16 v[10:13], v[134:137], v[174:177], v[10:13]
	v_mfma_f32_16x16x32_bf16 v[18:21], v[142:145], v[174:177], v[18:21]
	v_mfma_f32_16x16x32_bf16 v[38:41], v[134:137], v[182:185], v[38:41]
	v_mfma_f32_16x16x32_bf16 v[42:45], v[142:145], v[182:185], v[42:45]
	v_mfma_f32_16x16x32_bf16 v[70:73], v[134:137], v[190:193], v[70:73]
	v_mfma_f32_16x16x32_bf16 v[74:77], v[142:145], v[190:193], v[74:77]
	v_mfma_f32_16x16x32_bf16 v[46:49], v[138:141], v[170:173], v[46:49]
	v_mfma_f32_16x16x32_bf16 v[50:53], v[146:149], v[170:173], v[50:53]
	v_mfma_f32_16x16x32_bf16 v[10:13], v[138:141], v[178:181], v[10:13]
	v_mfma_f32_16x16x32_bf16 v[18:21], v[146:149], v[178:181], v[18:21]
	v_mfma_f32_16x16x32_bf16 v[38:41], v[138:141], v[186:189], v[38:41]
	v_mfma_f32_16x16x32_bf16 v[42:45], v[146:149], v[186:189], v[42:45]
	v_mfma_f32_16x16x32_bf16 v[70:73], v[138:141], v[194:197], v[70:73]
	v_mfma_f32_16x16x32_bf16 v[74:77], v[146:149], v[194:197], v[74:77]
	s_setprio 0
	s_barrier
	ds_read_b128 v[190:193], v236 offset:16384
	ds_read_b128 v[194:197], v236 offset:17408
	ds_read_b128 v[182:185], v236 offset:18432
	ds_read_b128 v[186:189], v236 offset:19456
	ds_read_b128 v[174:177], v236 offset:20480
	ds_read_b128 v[178:181], v236 offset:21504
	ds_read_b128 v[166:169], v236 offset:22528
	ds_read_b128 v[170:173], v236 offset:23552
	s_and_b64 s[10:11], s[58:59], s[10:11]
	s_mov_b64 s[66:67], -1
	s_and_b64 vcc, exec, s[10:11]
	v_lshl_add_u64 v[230:231], s[62:63], 0, v[200:201]
	v_lshl_add_u64 v[228:229], s[62:63], 0, v[14:15]
	v_lshl_add_u64 v[226:227], s[64:65], 0, v[202:203]
	v_lshl_add_u64 v[224:225], s[64:65], 0, v[198:199]
	s_cbranch_vccnz .LBB0_1313
	s_mov_b32 m0, s22
	s_add_u32 s66, s62, s0
	global_load_lds_dwordx4 v[230:231], off
	s_mov_b32 m0, s23
	s_addc_u32 s67, s63, 0
	global_load_lds_dwordx4 v[228:229], off
	v_lshl_add_u64 v[240:241], s[66:67], 0, v[200:201]
	s_mov_b32 m0, s25
	s_nop 0
	global_load_lds_dwordx4 v[240:241], off
	v_lshl_add_u64 v[240:241], s[66:67], 0, v[14:15]
	s_mov_b32 m0, s28
	s_mov_b64 s[66:67], 0
	global_load_lds_dwordx4 v[240:241], off
	s_mov_b32 m0, s21
	s_nop 0
	global_load_lds_dwordx4 v[226:227], off
	s_mov_b32 m0, s29
	s_nop 0
	global_load_lds_dwordx4 v[224:225], off
	s_waitcnt vmcnt(8)

.LBB0_1315:
	s_waitcnt lgkmcnt(0)
	s_xor_b64 s[66:67], s[10:11], -1
	s_barrier
	s_setprio 1
	s_waitcnt lgkmcnt(0)
	v_mfma_f32_16x16x32_bf16 v[78:81], v[150:153], v[190:193], v[78:81]
	v_mfma_f32_16x16x32_bf16 v[86:89], v[158:161], v[190:193], v[86:89]
	v_mfma_f32_16x16x32_bf16 v[110:113], v[150:153], v[182:185], v[110:113]
	v_mfma_f32_16x16x32_bf16 v[114:117], v[158:161], v[182:185], v[114:117]
	v_mfma_f32_16x16x32_bf16 v[130:133], v[150:153], v[174:177], v[130:133]
	v_mfma_f32_16x16x32_bf16 v[118:121], v[158:161], v[174:177], v[118:121]
	v_mfma_f32_16x16x32_bf16 v[90:93], v[150:153], v[166:169], v[90:93]
	v_mfma_f32_16x16x32_bf16 v[82:85], v[158:161], v[166:169], v[82:85]
	v_mfma_f32_16x16x32_bf16 v[78:81], v[154:157], v[194:197], v[78:81]
	v_mfma_f32_16x16x32_bf16 v[86:89], v[162:165], v[194:197], v[86:89]
	v_mfma_f32_16x16x32_bf16 v[110:113], v[154:157], v[186:189], v[110:113]
	v_mfma_f32_16x16x32_bf16 v[114:117], v[162:165], v[186:189], v[114:117]
	v_mfma_f32_16x16x32_bf16 v[130:133], v[154:157], v[178:181], v[130:133]
	v_mfma_f32_16x16x32_bf16 v[118:121], v[162:165], v[178:181], v[118:121]
	v_mfma_f32_16x16x32_bf16 v[90:93], v[154:157], v[170:173], v[90:93]
	v_mfma_f32_16x16x32_bf16 v[82:85], v[162:165], v[170:173], v[82:85]
	v_mfma_f32_16x16x32_bf16 v[94:97], v[134:137], v[190:193], v[94:97]
	v_mfma_f32_16x16x32_bf16 v[98:101], v[142:145], v[190:193], v[98:101]
	v_mfma_f32_16x16x32_bf16 v[122:125], v[134:137], v[182:185], v[122:125]
	v_mfma_f32_16x16x32_bf16 v[126:129], v[142:145], v[182:185], v[126:129]
	v_mfma_f32_16x16x32_bf16 v[106:109], v[134:137], v[174:177], v[106:109]
	v_mfma_f32_16x16x32_bf16 v[102:105], v[142:145], v[174:177], v[102:105]
	v_mfma_f32_16x16x32_bf16 v[66:69], v[134:137], v[166:169], v[66:69]
	v_mfma_f32_16x16x32_bf16 v[62:65], v[142:145], v[166:169], v[62:65]
	v_mfma_f32_16x16x32_bf16 v[94:97], v[138:141], v[194:197], v[94:97]
	v_mfma_f32_16x16x32_bf16 v[98:101], v[146:149], v[194:197], v[98:101]
	v_mfma_f32_16x16x32_bf16 v[122:125], v[138:141], v[186:189], v[122:125]
	v_mfma_f32_16x16x32_bf16 v[126:129], v[146:149], v[186:189], v[126:129]
	v_mfma_f32_16x16x32_bf16 v[106:109], v[138:141], v[178:181], v[106:109]
	v_mfma_f32_16x16x32_bf16 v[102:105], v[146:149], v[178:181], v[102:105]
	v_mfma_f32_16x16x32_bf16 v[66:69], v[138:141], v[170:173], v[66:69]
	v_mfma_f32_16x16x32_bf16 v[62:65], v[146:149], v[170:173], v[62:65]
	s_setprio 0
	s_barrier
	v_add_u32_e32 v0, 0x18000, v235
	ds_read_b128 v[150:153], v0
	ds_read_b128 v[154:157], v0 offset:1024
	ds_read_b128 v[158:161], v0 offset:2048
	ds_read_b128 v[162:165], v0 offset:3072
	v_add_u32_e32 v0, 0x1c000, v235
	ds_read_b128 v[134:137], v0
	ds_read_b128 v[138:141], v0 offset:1024
	ds_read_b128 v[142:145], v0 offset:2048
	ds_read_b128 v[146:149], v0 offset:3072
	ds_read_b128 v[190:193], v236 offset:32768
	ds_read_b128 v[194:197], v236 offset:33792
	ds_read_b128 v[182:185], v236 offset:34816
	ds_read_b128 v[186:189], v236 offset:35840
	ds_read_b128 v[174:177], v236 offset:36864
	ds_read_b128 v[178:181], v236 offset:37888
	ds_read_b128 v[166:169], v236 offset:38912
	ds_read_b128 v[170:173], v236 offset:39936
	v_cndmask_b32_e64 v0, 0, 1, s[66:67]
	v_cmp_ne_u32_e64 s[10:11], 1, v0
	s_andn2_b64 vcc, exec, s[66:67]
	s_mov_b64 s[66:67], -1
	s_cbranch_vccnz .LBB0_1317
	s_add_u32 s64, s64, s0
	s_addc_u32 s65, s65, 0
	s_mov_b32 m0, s36
	v_lshl_add_u64 v[240:241], s[64:65], 0, v[202:203]
	global_load_lds_dwordx4 v[240:241], off
	v_lshl_add_u64 v[240:241], s[64:65], 0, v[198:199]
	s_mov_b32 m0, s38
	s_mov_b64 s[66:67], 0
	global_load_lds_dwordx4 v[240:241], off
	s_waitcnt vmcnt(8)

.LBB0_1319:
	s_waitcnt lgkmcnt(0)
	s_barrier
	s_setprio 1
	s_waitcnt lgkmcnt(0)
	v_mfma_f32_16x16x32_bf16 v[30:33], v[150:153], v[190:193], v[30:33]
	v_mfma_f32_16x16x32_bf16 v[34:37], v[158:161], v[190:193], v[34:37]
	v_mfma_f32_16x16x32_bf16 v[6:9], v[150:153], v[182:185], v[6:9]
	v_mfma_f32_16x16x32_bf16 v[2:5], v[158:161], v[182:185], v[2:5]
	v_mfma_f32_16x16x32_bf16 v[22:25], v[150:153], v[174:177], v[22:25]
	v_mfma_f32_16x16x32_bf16 v[26:29], v[158:161], v[174:177], v[26:29]
	v_mfma_f32_16x16x32_bf16 v[54:57], v[150:153], v[166:169], v[54:57]
	v_mfma_f32_16x16x32_bf16 v[58:61], v[158:161], v[166:169], v[58:61]
	v_mfma_f32_16x16x32_bf16 v[30:33], v[154:157], v[194:197], v[30:33]
	v_mfma_f32_16x16x32_bf16 v[34:37], v[162:165], v[194:197], v[34:37]
	v_mfma_f32_16x16x32_bf16 v[6:9], v[154:157], v[186:189], v[6:9]
	v_mfma_f32_16x16x32_bf16 v[2:5], v[162:165], v[186:189], v[2:5]
	v_mfma_f32_16x16x32_bf16 v[22:25], v[154:157], v[178:181], v[22:25]
	v_mfma_f32_16x16x32_bf16 v[26:29], v[162:165], v[178:181], v[26:29]
	v_mfma_f32_16x16x32_bf16 v[54:57], v[154:157], v[170:173], v[54:57]
	v_mfma_f32_16x16x32_bf16 v[58:61], v[162:165], v[170:173], v[58:61]
	v_mfma_f32_16x16x32_bf16 v[46:49], v[134:137], v[190:193], v[46:49]
	v_mfma_f32_16x16x32_bf16 v[50:53], v[142:145], v[190:193], v[50:53]
	v_mfma_f32_16x16x32_bf16 v[10:13], v[134:137], v[182:185], v[10:13]
	v_mfma_f32_16x16x32_bf16 v[18:21], v[142:145], v[182:185], v[18:21]
	v_mfma_f32_16x16x32_bf16 v[38:41], v[134:137], v[174:177], v[38:41]
	v_mfma_f32_16x16x32_bf16 v[42:45], v[142:145], v[174:177], v[42:45]
	v_mfma_f32_16x16x32_bf16 v[70:73], v[134:137], v[166:169], v[70:73]
	v_mfma_f32_16x16x32_bf16 v[74:77], v[142:145], v[166:169], v[74:77]
	v_mfma_f32_16x16x32_bf16 v[46:49], v[138:141], v[194:197], v[46:49]
	v_mfma_f32_16x16x32_bf16 v[50:53], v[146:149], v[194:197], v[50:53]
	v_mfma_f32_16x16x32_bf16 v[10:13], v[138:141], v[186:189], v[10:13]
	v_mfma_f32_16x16x32_bf16 v[18:21], v[146:149], v[186:189], v[18:21]
	v_mfma_f32_16x16x32_bf16 v[38:41], v[138:141], v[178:181], v[38:41]
	v_mfma_f32_16x16x32_bf16 v[42:45], v[146:149], v[178:181], v[42:45]
	v_mfma_f32_16x16x32_bf16 v[70:73], v[138:141], v[170:173], v[70:73]
	v_mfma_f32_16x16x32_bf16 v[74:77], v[146:149], v[170:173], v[74:77]
	s_setprio 0
	s_barrier
	ds_read_b128 v[190:193], v236 offset:49152
	ds_read_b128 v[194:197], v236 offset:50176
	ds_read_b128 v[182:185], v236 offset:51200
	ds_read_b128 v[186:189], v236 offset:52224
	ds_read_b128 v[174:177], v236 offset:53248
	ds_read_b128 v[178:181], v236 offset:54272
	ds_read_b128 v[166:169], v236 offset:55296
	ds_read_b128 v[170:173], v236 offset:56320
	s_and_b64 vcc, exec, s[10:11]
	s_cbranch_vccnz .LBB0_1310
	s_mov_b32 m0, s68
	v_lshl_add_u64 v[230:231], v[230:231], 0, s[16:17]
	s_add_u32 s10, s62, s0
	global_load_lds_dwordx4 v[230:231], off
	v_lshl_add_u64 v[228:229], v[228:229], 0, s[16:17]
	s_mov_b32 m0, s69
	s_addc_u32 s11, s63, 0
	global_load_lds_dwordx4 v[228:229], off
	v_lshl_add_u64 v[228:229], s[10:11], 0, v[200:201]
	v_lshl_add_u64 v[228:229], v[228:229], 0, s[16:17]
	s_mov_b32 m0, s72
	v_lshl_add_u64 v[226:227], v[226:227], 0, s[16:17]
	global_load_lds_dwordx4 v[228:229], off
	v_lshl_add_u64 v[228:229], s[10:11], 0, v[14:15]
	v_lshl_add_u64 v[228:229], v[228:229], 0, s[16:17]
	s_mov_b32 m0, s73
	v_lshl_add_u64 v[224:225], v[224:225], 0, s[16:17]
	global_load_lds_dwordx4 v[228:229], off
	s_mov_b32 m0, s70
	s_nop 0
	global_load_lds_dwordx4 v[226:227], off
	s_mov_b32 m0, s71
	s_nop 0
	global_load_lds_dwordx4 v[224:225], off
	s_waitcnt vmcnt(8)
	s_branch .LBB0_1310

.LBB0_1532:
	s_waitcnt lgkmcnt(0)
	s_barrier
	s_setprio 1
	s_waitcnt lgkmcnt(0)
	v_mfma_f32_16x16x32_bf16 v[66:69], v[150:153], v[190:193], v[66:69]
	v_mfma_f32_16x16x32_bf16 v[62:65], v[158:161], v[190:193], v[62:65]
	v_mfma_f32_16x16x32_bf16 v[50:53], v[150:153], v[182:185], v[50:53]
	v_mfma_f32_16x16x32_bf16 v[46:49], v[158:161], v[182:185], v[46:49]
	v_mfma_f32_16x16x32_bf16 v[34:37], v[150:153], v[174:177], v[34:37]
	v_mfma_f32_16x16x32_bf16 v[30:33], v[158:161], v[174:177], v[30:33]
	v_mfma_f32_16x16x32_bf16 v[18:21], v[150:153], v[166:169], v[18:21]
	v_mfma_f32_16x16x32_bf16 v[10:13], v[158:161], v[166:169], v[10:13]
	v_mfma_f32_16x16x32_bf16 v[66:69], v[154:157], v[194:197], v[66:69]
	v_mfma_f32_16x16x32_bf16 v[62:65], v[162:165], v[194:197], v[62:65]
	v_mfma_f32_16x16x32_bf16 v[50:53], v[154:157], v[186:189], v[50:53]
	v_mfma_f32_16x16x32_bf16 v[46:49], v[162:165], v[186:189], v[46:49]
	v_mfma_f32_16x16x32_bf16 v[34:37], v[154:157], v[178:181], v[34:37]
	v_mfma_f32_16x16x32_bf16 v[30:33], v[162:165], v[178:181], v[30:33]
	v_mfma_f32_16x16x32_bf16 v[18:21], v[154:157], v[170:173], v[18:21]
	v_mfma_f32_16x16x32_bf16 v[10:13], v[162:165], v[170:173], v[10:13]
	v_mfma_f32_16x16x32_bf16 v[58:61], v[134:137], v[190:193], v[58:61]
	v_mfma_f32_16x16x32_bf16 v[54:57], v[142:145], v[190:193], v[54:57]
	v_mfma_f32_16x16x32_bf16 v[42:45], v[134:137], v[182:185], v[42:45]
	v_mfma_f32_16x16x32_bf16 v[38:41], v[142:145], v[182:185], v[38:41]
	v_mfma_f32_16x16x32_bf16 v[26:29], v[134:137], v[174:177], v[26:29]
	v_mfma_f32_16x16x32_bf16 v[22:25], v[142:145], v[174:177], v[22:25]
	v_mfma_f32_16x16x32_bf16 v[6:9], v[134:137], v[166:169], v[6:9]
	v_mfma_f32_16x16x32_bf16 v[2:5], v[142:145], v[166:169], v[2:5]
	v_mfma_f32_16x16x32_bf16 v[58:61], v[138:141], v[194:197], v[58:61]
	v_mfma_f32_16x16x32_bf16 v[54:57], v[146:149], v[194:197], v[54:57]
	v_mfma_f32_16x16x32_bf16 v[42:45], v[138:141], v[186:189], v[42:45]
	v_mfma_f32_16x16x32_bf16 v[38:41], v[146:149], v[186:189], v[38:41]
	v_mfma_f32_16x16x32_bf16 v[26:29], v[138:141], v[178:181], v[26:29]
	v_mfma_f32_16x16x32_bf16 v[22:25], v[146:149], v[178:181], v[22:25]
	v_mfma_f32_16x16x32_bf16 v[6:9], v[138:141], v[170:173], v[6:9]
	v_mfma_f32_16x16x32_bf16 v[2:5], v[146:149], v[170:173], v[2:5]
	s_setprio 0
	s_barrier
	s_add_i32 s33, s33, 2
	s_add_u32 s48, s48, 0x100
	s_addc_u32 s49, s49, 0
	s_add_u32 s70, s70, 0x100
	s_addc_u32 s71, s71, 0
	s_cmp_gt_u32 s33, 29
	s_cbranch_scc1 .LBB0_1543
.LBB0_1533:
	v_add_u32_e32 v134, 0x10000, v218
	v_add_u32_e32 v146, 0x14000, v218
	ds_read_b128 v[150:153], v134
	ds_read_b128 v[154:157], v134 offset:1024
	ds_read_b128 v[158:161], v134 offset:2048
	ds_read_b128 v[162:165], v134 offset:3072
	ds_read_b128 v[134:137], v146
	ds_read_b128 v[138:141], v146 offset:1024
	ds_read_b128 v[142:145], v146 offset:2048
	ds_read_b128 v[146:149], v146 offset:3072
	s_add_u32 s52, s48, 0xfff80080
	s_addc_u32 s53, s49, -1
	s_cmp_lg_u32 s33, 28
	s_cselect_b64 s[54:55], -1, 0
	s_and_b64 s[50:51], s[54:55], exec
	s_cselect_b32 s51, s71, s11
	s_cselect_b32 s50, s70, s69
	s_cselect_b32 s53, s53, s13
	s_cselect_b32 s52, s52, s68
	v_lshl_add_u64 v[208:209], s[48:49], 0, v[204:205]
	s_add_i32 m0, s22, 0xc000
	ds_read_b128 v[166:169], v219
	ds_read_b128 v[170:173], v219 offset:1024
	ds_read_b128 v[174:177], v219 offset:2048
	ds_read_b128 v[178:181], v219 offset:3072
	ds_read_b128 v[182:185], v219 offset:4096
	ds_read_b128 v[186:189], v219 offset:5120
	ds_read_b128 v[190:193], v219 offset:6144
	ds_read_b128 v[194:197], v219 offset:7168
	global_load_lds_dwordx4 v[208:209], off
	v_lshl_add_u64 v[208:209], s[48:49], 0, v[206:207]
	s_add_i32 m0, s22, 0xe000
	s_nop 0
	global_load_lds_dwordx4 v[208:209], off
	s_waitcnt vmcnt(8)
	s_waitcnt lgkmcnt(0)
	s_barrier
	s_setprio 1
	s_waitcnt lgkmcnt(0)
	v_mfma_f32_16x16x32_bf16 v[130:133], v[150:153], v[166:169], v[130:133]
	v_mfma_f32_16x16x32_bf16 v[126:129], v[158:161], v[166:169], v[126:129]
	v_mfma_f32_16x16x32_bf16 v[114:117], v[150:153], v[174:177], v[114:117]
	v_mfma_f32_16x16x32_bf16 v[110:113], v[158:161], v[174:177], v[110:113]
	v_mfma_f32_16x16x32_bf16 v[98:101], v[150:153], v[182:185], v[98:101]
	v_mfma_f32_16x16x32_bf16 v[94:97], v[158:161], v[182:185], v[94:97]
	v_mfma_f32_16x16x32_bf16 v[82:85], v[150:153], v[190:193], v[82:85]
	v_mfma_f32_16x16x32_bf16 v[78:81], v[158:161], v[190:193], v[78:81]
	v_mfma_f32_16x16x32_bf16 v[130:133], v[154:157], v[170:173], v[130:133]
	v_mfma_f32_16x16x32_bf16 v[126:129], v[162:165], v[170:173], v[126:129]
	v_mfma_f32_16x16x32_bf16 v[114:117], v[154:157], v[178:181], v[114:117]
	v_mfma_f32_16x16x32_bf16 v[110:113], v[162:165], v[178:181], v[110:113]
	v_mfma_f32_16x16x32_bf16 v[98:101], v[154:157], v[186:189], v[98:101]
	v_mfma_f32_16x16x32_bf16 v[94:97], v[162:165], v[186:189], v[94:97]
	v_mfma_f32_16x16x32_bf16 v[82:85], v[154:157], v[194:197], v[82:85]
	v_mfma_f32_16x16x32_bf16 v[78:81], v[162:165], v[194:197], v[78:81]
	v_mfma_f32_16x16x32_bf16 v[122:125], v[134:137], v[166:169], v[122:125]
	v_mfma_f32_16x16x32_bf16 v[118:121], v[142:145], v[166:169], v[118:121]
	v_mfma_f32_16x16x32_bf16 v[106:109], v[134:137], v[174:177], v[106:109]
	v_mfma_f32_16x16x32_bf16 v[102:105], v[142:145], v[174:177], v[102:105]
	v_mfma_f32_16x16x32_bf16 v[90:93], v[134:137], v[182:185], v[90:93]
	v_mfma_f32_16x16x32_bf16 v[86:89], v[142:145], v[182:185], v[86:89]
	v_mfma_f32_16x16x32_bf16 v[74:77], v[134:137], v[190:193], v[74:77]
	v_mfma_f32_16x16x32_bf16 v[70:73], v[142:145], v[190:193], v[70:73]
	v_mfma_f32_16x16x32_bf16 v[122:125], v[138:141], v[170:173], v[122:125]
	v_mfma_f32_16x16x32_bf16 v[118:121], v[146:149], v[170:173], v[118:121]
	v_mfma_f32_16x16x32_bf16 v[106:109], v[138:141], v[178:181], v[106:109]
	v_mfma_f32_16x16x32_bf16 v[102:105], v[146:149], v[178:181], v[102:105]
	v_mfma_f32_16x16x32_bf16 v[90:93], v[138:141], v[186:189], v[90:93]
	v_mfma_f32_16x16x32_bf16 v[86:89], v[146:149], v[186:189], v[86:89]
	v_mfma_f32_16x16x32_bf16 v[74:77], v[138:141], v[194:197], v[74:77]
	v_mfma_f32_16x16x32_bf16 v[70:73], v[146:149], v[194:197], v[70:73]
	s_setprio 0
	s_barrier
	ds_read_b128 v[190:193], v219 offset:16384
	ds_read_b128 v[194:197], v219 offset:17408
	ds_read_b128 v[182:185], v219 offset:18432
	ds_read_b128 v[186:189], v219 offset:19456
	ds_read_b128 v[174:177], v219 offset:20480
	ds_read_b128 v[178:181], v219 offset:21504
	ds_read_b128 v[166:169], v219 offset:22528
	ds_read_b128 v[170:173], v219 offset:23552
	s_or_b64 s[54:55], s[40:41], s[54:55]
	s_xor_b64 s[56:57], s[54:55], -1
	s_mov_b64 s[58:59], -1
	s_and_b64 vcc, exec, s[56:57]
	s_cbranch_vccz .LBB0_1535
	s_waitcnt vmcnt(2)
	s_mov_b64 s[58:59], 0

.LBB0_1537:
	s_waitcnt lgkmcnt(0)
	s_barrier
	s_setprio 1
	s_waitcnt lgkmcnt(0)
	v_mfma_f32_16x16x32_bf16 v[66:69], v[150:153], v[190:193], v[66:69]
	v_mfma_f32_16x16x32_bf16 v[62:65], v[158:161], v[190:193], v[62:65]
	v_mfma_f32_16x16x32_bf16 v[50:53], v[150:153], v[182:185], v[50:53]
	v_mfma_f32_16x16x32_bf16 v[46:49], v[158:161], v[182:185], v[46:49]
	v_mfma_f32_16x16x32_bf16 v[34:37], v[150:153], v[174:177], v[34:37]
	v_mfma_f32_16x16x32_bf16 v[30:33], v[158:161], v[174:177], v[30:33]
	v_mfma_f32_16x16x32_bf16 v[18:21], v[150:153], v[166:169], v[18:21]
	v_mfma_f32_16x16x32_bf16 v[10:13], v[158:161], v[166:169], v[10:13]
	v_mfma_f32_16x16x32_bf16 v[66:69], v[154:157], v[194:197], v[66:69]
	v_mfma_f32_16x16x32_bf16 v[62:65], v[162:165], v[194:197], v[62:65]
	v_mfma_f32_16x16x32_bf16 v[50:53], v[154:157], v[186:189], v[50:53]
	v_mfma_f32_16x16x32_bf16 v[46:49], v[162:165], v[186:189], v[46:49]
	v_mfma_f32_16x16x32_bf16 v[34:37], v[154:157], v[178:181], v[34:37]
	v_mfma_f32_16x16x32_bf16 v[30:33], v[162:165], v[178:181], v[30:33]
	v_mfma_f32_16x16x32_bf16 v[18:21], v[154:157], v[170:173], v[18:21]
	v_mfma_f32_16x16x32_bf16 v[10:13], v[162:165], v[170:173], v[10:13]
	v_mfma_f32_16x16x32_bf16 v[58:61], v[134:137], v[190:193], v[58:61]
	v_mfma_f32_16x16x32_bf16 v[54:57], v[142:145], v[190:193], v[54:57]
	v_mfma_f32_16x16x32_bf16 v[42:45], v[134:137], v[182:185], v[42:45]
	v_mfma_f32_16x16x32_bf16 v[38:41], v[142:145], v[182:185], v[38:41]
	v_mfma_f32_16x16x32_bf16 v[26:29], v[134:137], v[174:177], v[26:29]
	v_mfma_f32_16x16x32_bf16 v[22:25], v[142:145], v[174:177], v[22:25]
	v_mfma_f32_16x16x32_bf16 v[6:9], v[134:137], v[166:169], v[6:9]
	v_mfma_f32_16x16x32_bf16 v[2:5], v[142:145], v[166:169], v[2:5]
	v_mfma_f32_16x16x32_bf16 v[58:61], v[138:141], v[194:197], v[58:61]
	v_mfma_f32_16x16x32_bf16 v[54:57], v[146:149], v[194:197], v[54:57]
	v_mfma_f32_16x16x32_bf16 v[42:45], v[138:141], v[186:189], v[42:45]
	v_mfma_f32_16x16x32_bf16 v[38:41], v[146:149], v[186:189], v[38:41]
	v_mfma_f32_16x16x32_bf16 v[26:29], v[138:141], v[178:181], v[26:29]
	v_mfma_f32_16x16x32_bf16 v[22:25], v[146:149], v[178:181], v[22:25]
	v_mfma_f32_16x16x32_bf16 v[6:9], v[138:141], v[170:173], v[6:9]
	v_mfma_f32_16x16x32_bf16 v[2:5], v[146:149], v[170:173], v[2:5]
	s_setprio 0
	s_barrier
	v_add_u32_e32 v134, 0x18000, v218
	v_add_u32_e32 v146, 0x1c000, v218
	ds_read_b128 v[150:153], v134
	ds_read_b128 v[154:157], v134 offset:1024
	ds_read_b128 v[158:161], v134 offset:2048
	ds_read_b128 v[162:165], v134 offset:3072
	ds_read_b128 v[134:137], v146
	ds_read_b128 v[138:141], v146 offset:1024
	ds_read_b128 v[142:145], v146 offset:2048
	ds_read_b128 v[146:149], v146 offset:3072
	ds_read_b128 v[190:193], v219 offset:32768
	ds_read_b128 v[194:197], v219 offset:33792
	ds_read_b128 v[182:185], v219 offset:34816
	ds_read_b128 v[186:189], v219 offset:35840
	ds_read_b128 v[174:177], v219 offset:36864
	ds_read_b128 v[178:181], v219 offset:37888
	ds_read_b128 v[166:169], v219 offset:38912
	ds_read_b128 v[170:173], v219 offset:39936
	s_mov_b64 s[58:59], -1
	s_and_b64 vcc, exec, s[56:57]
	s_cbranch_vccz .LBB0_1539
	s_waitcnt vmcnt(0)
	s_mov_b64 s[58:59], 0

.LBB0_1541:
	s_waitcnt lgkmcnt(0)
	s_barrier
	s_setprio 1
	s_waitcnt lgkmcnt(0)
	v_mfma_f32_16x16x32_bf16 v[130:133], v[150:153], v[190:193], v[130:133]
	v_mfma_f32_16x16x32_bf16 v[126:129], v[158:161], v[190:193], v[126:129]
	v_mfma_f32_16x16x32_bf16 v[114:117], v[150:153], v[182:185], v[114:117]
	v_mfma_f32_16x16x32_bf16 v[110:113], v[158:161], v[182:185], v[110:113]
	v_mfma_f32_16x16x32_bf16 v[98:101], v[150:153], v[174:177], v[98:101]
	v_mfma_f32_16x16x32_bf16 v[94:97], v[158:161], v[174:177], v[94:97]
	v_mfma_f32_16x16x32_bf16 v[82:85], v[150:153], v[166:169], v[82:85]
	v_mfma_f32_16x16x32_bf16 v[78:81], v[158:161], v[166:169], v[78:81]
	v_mfma_f32_16x16x32_bf16 v[130:133], v[154:157], v[194:197], v[130:133]
	v_mfma_f32_16x16x32_bf16 v[126:129], v[162:165], v[194:197], v[126:129]
	v_mfma_f32_16x16x32_bf16 v[114:117], v[154:157], v[186:189], v[114:117]
	v_mfma_f32_16x16x32_bf16 v[110:113], v[162:165], v[186:189], v[110:113]
	v_mfma_f32_16x16x32_bf16 v[98:101], v[154:157], v[178:181], v[98:101]
	v_mfma_f32_16x16x32_bf16 v[94:97], v[162:165], v[178:181], v[94:97]
	v_mfma_f32_16x16x32_bf16 v[82:85], v[154:157], v[170:173], v[82:85]
	v_mfma_f32_16x16x32_bf16 v[78:81], v[162:165], v[170:173], v[78:81]
	v_mfma_f32_16x16x32_bf16 v[122:125], v[134:137], v[190:193], v[122:125]
	v_mfma_f32_16x16x32_bf16 v[118:121], v[142:145], v[190:193], v[118:121]
	v_mfma_f32_16x16x32_bf16 v[106:109], v[134:137], v[182:185], v[106:109]
	v_mfma_f32_16x16x32_bf16 v[102:105], v[142:145], v[182:185], v[102:105]
	v_mfma_f32_16x16x32_bf16 v[90:93], v[134:137], v[174:177], v[90:93]
	v_mfma_f32_16x16x32_bf16 v[86:89], v[142:145], v[174:177], v[86:89]
	v_mfma_f32_16x16x32_bf16 v[74:77], v[134:137], v[166:169], v[74:77]
	v_mfma_f32_16x16x32_bf16 v[70:73], v[142:145], v[166:169], v[70:73]
	v_mfma_f32_16x16x32_bf16 v[122:125], v[138:141], v[194:197], v[122:125]
	v_mfma_f32_16x16x32_bf16 v[118:121], v[146:149], v[194:197], v[118:121]
	v_mfma_f32_16x16x32_bf16 v[106:109], v[138:141], v[186:189], v[106:109]
	v_mfma_f32_16x16x32_bf16 v[102:105], v[146:149], v[186:189], v[102:105]
	v_mfma_f32_16x16x32_bf16 v[90:93], v[138:141], v[178:181], v[90:93]
	v_mfma_f32_16x16x32_bf16 v[86:89], v[146:149], v[178:181], v[86:89]
	v_mfma_f32_16x16x32_bf16 v[74:77], v[138:141], v[170:173], v[74:77]
	v_mfma_f32_16x16x32_bf16 v[70:73], v[146:149], v[170:173], v[70:73]
	s_setprio 0
	s_barrier
	ds_read_b128 v[190:193], v219 offset:49152
	ds_read_b128 v[194:197], v219 offset:50176
	ds_read_b128 v[182:185], v219 offset:51200
	ds_read_b128 v[186:189], v219 offset:52224
	ds_read_b128 v[174:177], v219 offset:53248
	ds_read_b128 v[178:181], v219 offset:54272
	ds_read_b128 v[166:169], v219 offset:55296
	ds_read_b128 v[170:173], v219 offset:56320
	s_andn2_b64 vcc, exec, s[54:55]
	s_cbranch_vccnz .LBB0_1532
	s_mov_b32 m0, s47
	v_lshl_add_u64 v[216:217], v[216:217], 0, s[16:17]
	s_add_u32 s50, s50, 0x80080
	global_load_lds_dwordx4 v[216:217], off
	v_lshl_add_u64 v[212:213], v[212:213], 0, s[16:17]
	s_mov_b32 m0, s60
	s_addc_u32 s51, s51, 0
	global_load_lds_dwordx4 v[212:213], off
	v_lshl_add_u64 v[212:213], s[50:51], 0, v[198:199]
	s_mov_b32 m0, s63
	v_lshl_add_u64 v[210:211], v[210:211], 0, s[16:17]
	global_load_lds_dwordx4 v[212:213], off
	v_lshl_add_u64 v[212:213], s[50:51], 0, v[202:203]
	s_mov_b32 m0, s64
	v_lshl_add_u64 v[208:209], v[208:209], 0, s[16:17]
	global_load_lds_dwordx4 v[212:213], off
	s_mov_b32 m0, s61
	s_nop 0
	global_load_lds_dwordx4 v[210:211], off
	s_mov_b32 m0, s62
	s_nop 0
	global_load_lds_dwordx4 v[208:209], off
	s_waitcnt vmcnt(8)
	s_branch .LBB0_1532

.LBB0_1632:
	s_waitcnt lgkmcnt(0)
	s_barrier
	s_setprio 1
	s_waitcnt lgkmcnt(0)
	v_mfma_f32_16x16x32_bf16 v[70:73], v[150:153], v[190:193], v[70:73]
	v_mfma_f32_16x16x32_bf16 v[74:77], v[158:161], v[190:193], v[74:77]
	v_mfma_f32_16x16x32_bf16 v[86:89], v[150:153], v[182:185], v[86:89]
	v_mfma_f32_16x16x32_bf16 v[90:93], v[158:161], v[182:185], v[90:93]
	v_mfma_f32_16x16x32_bf16 v[102:105], v[150:153], v[174:177], v[102:105]
	v_mfma_f32_16x16x32_bf16 v[106:109], v[158:161], v[174:177], v[106:109]
	v_mfma_f32_16x16x32_bf16 v[118:121], v[150:153], v[166:169], v[118:121]
	v_mfma_f32_16x16x32_bf16 v[122:125], v[158:161], v[166:169], v[122:125]
	v_mfma_f32_16x16x32_bf16 v[70:73], v[154:157], v[194:197], v[70:73]
	v_mfma_f32_16x16x32_bf16 v[74:77], v[162:165], v[194:197], v[74:77]
	v_mfma_f32_16x16x32_bf16 v[86:89], v[154:157], v[186:189], v[86:89]
	v_mfma_f32_16x16x32_bf16 v[90:93], v[162:165], v[186:189], v[90:93]
	v_mfma_f32_16x16x32_bf16 v[102:105], v[154:157], v[178:181], v[102:105]
	v_mfma_f32_16x16x32_bf16 v[106:109], v[162:165], v[178:181], v[106:109]
	v_mfma_f32_16x16x32_bf16 v[118:121], v[154:157], v[170:173], v[118:121]
	v_mfma_f32_16x16x32_bf16 v[122:125], v[162:165], v[170:173], v[122:125]
	v_mfma_f32_16x16x32_bf16 v[82:85], v[134:137], v[190:193], v[82:85]
	v_mfma_f32_16x16x32_bf16 v[78:81], v[142:145], v[190:193], v[78:81]
	v_mfma_f32_16x16x32_bf16 v[98:101], v[134:137], v[182:185], v[98:101]
	v_mfma_f32_16x16x32_bf16 v[94:97], v[142:145], v[182:185], v[94:97]
	v_mfma_f32_16x16x32_bf16 v[114:117], v[134:137], v[174:177], v[114:117]
	v_mfma_f32_16x16x32_bf16 v[110:113], v[142:145], v[174:177], v[110:113]
	v_mfma_f32_16x16x32_bf16 v[130:133], v[134:137], v[166:169], v[130:133]
	v_mfma_f32_16x16x32_bf16 v[126:129], v[142:145], v[166:169], v[126:129]
	v_mfma_f32_16x16x32_bf16 v[82:85], v[138:141], v[194:197], v[82:85]
	v_mfma_f32_16x16x32_bf16 v[78:81], v[146:149], v[194:197], v[78:81]
	v_mfma_f32_16x16x32_bf16 v[98:101], v[138:141], v[186:189], v[98:101]
	v_mfma_f32_16x16x32_bf16 v[94:97], v[146:149], v[186:189], v[94:97]
	v_mfma_f32_16x16x32_bf16 v[114:117], v[138:141], v[178:181], v[114:117]
	v_mfma_f32_16x16x32_bf16 v[110:113], v[146:149], v[178:181], v[110:113]
	v_mfma_f32_16x16x32_bf16 v[130:133], v[138:141], v[170:173], v[130:133]
	v_mfma_f32_16x16x32_bf16 v[126:129], v[146:149], v[170:173], v[126:129]
	s_setprio 0
	s_barrier
	s_add_i32 s25, s25, 2
	s_cmpk_gt_u32 s25, 0x7d
	s_cbranch_scc1 .LBB0_1643
.LBB0_1633:
	s_mov_b64 s[10:11], s[66:67]
	s_add_u32 s66, s10, 0x100
	s_addc_u32 s67, s11, 0
	v_add_u32_e32 v0, 0x10000, v250
	s_add_u32 s28, s14, s10
	ds_read_b128 v[150:153], v0
	ds_read_b128 v[154:157], v0 offset:1024
	ds_read_b128 v[158:161], v0 offset:2048
	ds_read_b128 v[162:165], v0 offset:3072
	v_add_u32_e32 v0, 0x14000, v250
	s_addc_u32 s33, s23, s11
	ds_read_b128 v[134:137], v0
	ds_read_b128 v[138:141], v0 offset:1024
	ds_read_b128 v[142:145], v0 offset:2048
	ds_read_b128 v[146:149], v0 offset:3072
	s_cmpk_eq_i32 s25, 0x7c
	s_cselect_b64 s[72:73], -1, 0
	s_and_b64 s[68:69], s[72:73], exec
	s_cselect_b32 s61, 0, s66
	s_cselect_b32 s38, 0, s67
	s_cselect_b32 s71, s0, s33
	s_cselect_b32 s70, s2, s28
	s_add_u32 s68, s48, s61
	s_addc_u32 s69, s49, s38
	v_lshl_add_u64 v[230:231], v[226:227], 0, s[10:11]
	s_add_i32 m0, s47, 0xc000
	ds_read_b128 v[166:169], v251
	ds_read_b128 v[170:173], v251 offset:1024
	ds_read_b128 v[174:177], v251 offset:2048
	ds_read_b128 v[178:181], v251 offset:3072
	ds_read_b128 v[182:185], v251 offset:4096
	ds_read_b128 v[186:189], v251 offset:5120
	ds_read_b128 v[190:193], v251 offset:6144
	ds_read_b128 v[194:197], v251 offset:7168
	global_load_lds_dwordx4 v[230:231], off
	v_lshl_add_u64 v[230:231], v[228:229], 0, s[10:11]
	s_add_i32 m0, s47, 0xe000
	s_nop 0
	global_load_lds_dwordx4 v[230:231], off
	s_waitcnt vmcnt(8)
	s_waitcnt lgkmcnt(0)
	s_barrier
	s_setprio 1
	s_waitcnt lgkmcnt(0)
	v_mfma_f32_16x16x32_bf16 v[22:25], v[150:153], v[166:169], v[22:25]
	v_mfma_f32_16x16x32_bf16 v[26:29], v[158:161], v[166:169], v[26:29]
	v_mfma_f32_16x16x32_bf16 v[18:21], v[150:153], v[174:177], v[18:21]
	v_mfma_f32_16x16x32_bf16 v[10:13], v[158:161], v[174:177], v[10:13]
	v_mfma_f32_16x16x32_bf16 v[30:33], v[150:153], v[182:185], v[30:33]
	v_mfma_f32_16x16x32_bf16 v[34:37], v[158:161], v[182:185], v[34:37]
	v_mfma_f32_16x16x32_bf16 v[54:57], v[150:153], v[190:193], v[54:57]
	v_mfma_f32_16x16x32_bf16 v[58:61], v[158:161], v[190:193], v[58:61]
	v_mfma_f32_16x16x32_bf16 v[22:25], v[154:157], v[170:173], v[22:25]
	v_mfma_f32_16x16x32_bf16 v[26:29], v[162:165], v[170:173], v[26:29]
	v_mfma_f32_16x16x32_bf16 v[18:21], v[154:157], v[178:181], v[18:21]
	v_mfma_f32_16x16x32_bf16 v[10:13], v[162:165], v[178:181], v[10:13]
	v_mfma_f32_16x16x32_bf16 v[30:33], v[154:157], v[186:189], v[30:33]
	v_mfma_f32_16x16x32_bf16 v[34:37], v[162:165], v[186:189], v[34:37]
	v_mfma_f32_16x16x32_bf16 v[54:57], v[154:157], v[194:197], v[54:57]
	v_mfma_f32_16x16x32_bf16 v[58:61], v[162:165], v[194:197], v[58:61]
	v_mfma_f32_16x16x32_bf16 v[50:53], v[134:137], v[166:169], v[50:53]
	v_mfma_f32_16x16x32_bf16 v[46:49], v[142:145], v[166:169], v[46:49]
	v_mfma_f32_16x16x32_bf16 v[6:9], v[134:137], v[174:177], v[6:9]
	v_mfma_f32_16x16x32_bf16 v[2:5], v[142:145], v[174:177], v[2:5]
	v_mfma_f32_16x16x32_bf16 v[42:45], v[134:137], v[182:185], v[42:45]
	v_mfma_f32_16x16x32_bf16 v[38:41], v[142:145], v[182:185], v[38:41]
	v_mfma_f32_16x16x32_bf16 v[66:69], v[134:137], v[190:193], v[66:69]
	v_mfma_f32_16x16x32_bf16 v[62:65], v[142:145], v[190:193], v[62:65]
	v_mfma_f32_16x16x32_bf16 v[50:53], v[138:141], v[170:173], v[50:53]
	v_mfma_f32_16x16x32_bf16 v[46:49], v[146:149], v[170:173], v[46:49]
	v_mfma_f32_16x16x32_bf16 v[6:9], v[138:141], v[178:181], v[6:9]
	v_mfma_f32_16x16x32_bf16 v[2:5], v[146:149], v[178:181], v[2:5]
	v_mfma_f32_16x16x32_bf16 v[42:45], v[138:141], v[186:189], v[42:45]
	v_mfma_f32_16x16x32_bf16 v[38:41], v[146:149], v[186:189], v[38:41]
	v_mfma_f32_16x16x32_bf16 v[66:69], v[138:141], v[194:197], v[66:69]
	v_mfma_f32_16x16x32_bf16 v[62:65], v[146:149], v[194:197], v[62:65]
	s_setprio 0
	s_barrier
	ds_read_b128 v[190:193], v251 offset:16384
	ds_read_b128 v[194:197], v251 offset:17408
	ds_read_b128 v[182:185], v251 offset:18432
	ds_read_b128 v[186:189], v251 offset:19456
	ds_read_b128 v[174:177], v251 offset:20480
	ds_read_b128 v[178:181], v251 offset:21504
	ds_read_b128 v[166:169], v251 offset:22528
	ds_read_b128 v[170:173], v251 offset:23552
	s_and_b64 s[10:11], s[64:65], s[72:73]
	s_mov_b64 s[72:73], -1
	s_and_b64 vcc, exec, s[10:11]
	v_lshl_add_u64 v[236:237], s[68:69], 0, v[200:201]
	v_lshl_add_u64 v[234:235], s[68:69], 0, v[14:15]
	v_lshl_add_u64 v[232:233], s[70:71], 0, v[202:203]
	v_lshl_add_u64 v[230:231], s[70:71], 0, v[198:199]
	s_cbranch_vccnz .LBB0_1635
	s_mov_b32 m0, s82
	s_add_u32 s72, s68, 0x200000
	global_load_lds_dwordx4 v[236:237], off
	s_mov_b32 m0, s83
	s_addc_u32 s73, s69, 0
	global_load_lds_dwordx4 v[234:235], off
	v_lshl_add_u64 v[240:241], s[72:73], 0, v[200:201]
	s_mov_b32 m0, s84
	s_nop 0
	global_load_lds_dwordx4 v[240:241], off
	v_lshl_add_u64 v[240:241], s[72:73], 0, v[14:15]
	s_mov_b32 m0, s85
	s_mov_b64 s[72:73], 0
	global_load_lds_dwordx4 v[240:241], off
	s_mov_b32 m0, s47
	s_nop 0
	global_load_lds_dwordx4 v[232:233], off
	s_mov_b32 m0, s86
	s_nop 0
	global_load_lds_dwordx4 v[230:231], off
	s_waitcnt vmcnt(8)

.LBB0_1637:
	s_waitcnt lgkmcnt(0)
	s_xor_b64 s[72:73], s[10:11], -1
	s_barrier
	s_setprio 1
	s_waitcnt lgkmcnt(0)
	v_mfma_f32_16x16x32_bf16 v[70:73], v[150:153], v[190:193], v[70:73]
	v_mfma_f32_16x16x32_bf16 v[74:77], v[158:161], v[190:193], v[74:77]
	v_mfma_f32_16x16x32_bf16 v[86:89], v[150:153], v[182:185], v[86:89]
	v_mfma_f32_16x16x32_bf16 v[90:93], v[158:161], v[182:185], v[90:93]
	v_mfma_f32_16x16x32_bf16 v[102:105], v[150:153], v[174:177], v[102:105]
	v_mfma_f32_16x16x32_bf16 v[106:109], v[158:161], v[174:177], v[106:109]
	v_mfma_f32_16x16x32_bf16 v[118:121], v[150:153], v[166:169], v[118:121]
	v_mfma_f32_16x16x32_bf16 v[122:125], v[158:161], v[166:169], v[122:125]
	v_mfma_f32_16x16x32_bf16 v[70:73], v[154:157], v[194:197], v[70:73]
	v_mfma_f32_16x16x32_bf16 v[74:77], v[162:165], v[194:197], v[74:77]
	v_mfma_f32_16x16x32_bf16 v[86:89], v[154:157], v[186:189], v[86:89]
	v_mfma_f32_16x16x32_bf16 v[90:93], v[162:165], v[186:189], v[90:93]
	v_mfma_f32_16x16x32_bf16 v[102:105], v[154:157], v[178:181], v[102:105]
	v_mfma_f32_16x16x32_bf16 v[106:109], v[162:165], v[178:181], v[106:109]
	v_mfma_f32_16x16x32_bf16 v[118:121], v[154:157], v[170:173], v[118:121]
	v_mfma_f32_16x16x32_bf16 v[122:125], v[162:165], v[170:173], v[122:125]
	v_mfma_f32_16x16x32_bf16 v[82:85], v[134:137], v[190:193], v[82:85]
	v_mfma_f32_16x16x32_bf16 v[78:81], v[142:145], v[190:193], v[78:81]
	v_mfma_f32_16x16x32_bf16 v[98:101], v[134:137], v[182:185], v[98:101]
	v_mfma_f32_16x16x32_bf16 v[94:97], v[142:145], v[182:185], v[94:97]
	v_mfma_f32_16x16x32_bf16 v[114:117], v[134:137], v[174:177], v[114:117]
	v_mfma_f32_16x16x32_bf16 v[110:113], v[142:145], v[174:177], v[110:113]
	v_mfma_f32_16x16x32_bf16 v[130:133], v[134:137], v[166:169], v[130:133]
	v_mfma_f32_16x16x32_bf16 v[126:129], v[142:145], v[166:169], v[126:129]
	v_mfma_f32_16x16x32_bf16 v[82:85], v[138:141], v[194:197], v[82:85]
	v_mfma_f32_16x16x32_bf16 v[78:81], v[146:149], v[194:197], v[78:81]
	v_mfma_f32_16x16x32_bf16 v[98:101], v[138:141], v[186:189], v[98:101]
	v_mfma_f32_16x16x32_bf16 v[94:97], v[146:149], v[186:189], v[94:97]
	v_mfma_f32_16x16x32_bf16 v[114:117], v[138:141], v[178:181], v[114:117]
	v_mfma_f32_16x16x32_bf16 v[110:113], v[146:149], v[178:181], v[110:113]
	v_mfma_f32_16x16x32_bf16 v[130:133], v[138:141], v[170:173], v[130:133]
	v_mfma_f32_16x16x32_bf16 v[126:129], v[146:149], v[170:173], v[126:129]
	s_setprio 0
	s_barrier
	v_add_u32_e32 v0, 0x18000, v250
	ds_read_b128 v[150:153], v0
	ds_read_b128 v[154:157], v0 offset:1024
	ds_read_b128 v[158:161], v0 offset:2048
	ds_read_b128 v[162:165], v0 offset:3072
	v_add_u32_e32 v0, 0x1c000, v250
	ds_read_b128 v[134:137], v0
	ds_read_b128 v[138:141], v0 offset:1024
	ds_read_b128 v[142:145], v0 offset:2048
	ds_read_b128 v[146:149], v0 offset:3072
	ds_read_b128 v[190:193], v251 offset:32768
	ds_read_b128 v[194:197], v251 offset:33792
	ds_read_b128 v[182:185], v251 offset:34816
	ds_read_b128 v[186:189], v251 offset:35840
	ds_read_b128 v[174:177], v251 offset:36864
	ds_read_b128 v[178:181], v251 offset:37888
	ds_read_b128 v[166:169], v251 offset:38912
	ds_read_b128 v[170:173], v251 offset:39936
	v_cndmask_b32_e64 v0, 0, 1, s[72:73]
	v_cmp_ne_u32_e64 s[10:11], 1, v0
	s_andn2_b64 vcc, exec, s[72:73]
	s_mov_b64 s[72:73], -1
	s_cbranch_vccnz .LBB0_1639
	s_add_u32 s70, s70, 0x200000
	s_addc_u32 s71, s71, 0
	s_mov_b32 m0, s87
	v_lshl_add_u64 v[240:241], s[70:71], 0, v[202:203]
	global_load_lds_dwordx4 v[240:241], off
	v_lshl_add_u64 v[240:241], s[70:71], 0, v[198:199]
	s_mov_b32 m0, s88
	s_mov_b64 s[72:73], 0
	global_load_lds_dwordx4 v[240:241], off
	s_waitcnt vmcnt(8)

.LBB0_1641:
	s_waitcnt lgkmcnt(0)
	s_barrier
	s_setprio 1
	s_waitcnt lgkmcnt(0)
	v_mfma_f32_16x16x32_bf16 v[22:25], v[150:153], v[190:193], v[22:25]
	v_mfma_f32_16x16x32_bf16 v[26:29], v[158:161], v[190:193], v[26:29]
	v_mfma_f32_16x16x32_bf16 v[18:21], v[150:153], v[182:185], v[18:21]
	v_mfma_f32_16x16x32_bf16 v[10:13], v[158:161], v[182:185], v[10:13]
	v_mfma_f32_16x16x32_bf16 v[30:33], v[150:153], v[174:177], v[30:33]
	v_mfma_f32_16x16x32_bf16 v[34:37], v[158:161], v[174:177], v[34:37]
	v_mfma_f32_16x16x32_bf16 v[54:57], v[150:153], v[166:169], v[54:57]
	v_mfma_f32_16x16x32_bf16 v[58:61], v[158:161], v[166:169], v[58:61]
	v_mfma_f32_16x16x32_bf16 v[22:25], v[154:157], v[194:197], v[22:25]
	v_mfma_f32_16x16x32_bf16 v[26:29], v[162:165], v[194:197], v[26:29]
	v_mfma_f32_16x16x32_bf16 v[18:21], v[154:157], v[186:189], v[18:21]
	v_mfma_f32_16x16x32_bf16 v[10:13], v[162:165], v[186:189], v[10:13]
	v_mfma_f32_16x16x32_bf16 v[30:33], v[154:157], v[178:181], v[30:33]
	v_mfma_f32_16x16x32_bf16 v[34:37], v[162:165], v[178:181], v[34:37]
	v_mfma_f32_16x16x32_bf16 v[54:57], v[154:157], v[170:173], v[54:57]
	v_mfma_f32_16x16x32_bf16 v[58:61], v[162:165], v[170:173], v[58:61]
	v_mfma_f32_16x16x32_bf16 v[50:53], v[134:137], v[190:193], v[50:53]
	v_mfma_f32_16x16x32_bf16 v[46:49], v[142:145], v[190:193], v[46:49]
	v_mfma_f32_16x16x32_bf16 v[6:9], v[134:137], v[182:185], v[6:9]
	v_mfma_f32_16x16x32_bf16 v[2:5], v[142:145], v[182:185], v[2:5]
	v_mfma_f32_16x16x32_bf16 v[42:45], v[134:137], v[174:177], v[42:45]
	v_mfma_f32_16x16x32_bf16 v[38:41], v[142:145], v[174:177], v[38:41]
	v_mfma_f32_16x16x32_bf16 v[66:69], v[134:137], v[166:169], v[66:69]
	v_mfma_f32_16x16x32_bf16 v[62:65], v[142:145], v[166:169], v[62:65]
	v_mfma_f32_16x16x32_bf16 v[50:53], v[138:141], v[194:197], v[50:53]
	v_mfma_f32_16x16x32_bf16 v[46:49], v[146:149], v[194:197], v[46:49]
	v_mfma_f32_16x16x32_bf16 v[6:9], v[138:141], v[186:189], v[6:9]
	v_mfma_f32_16x16x32_bf16 v[2:5], v[146:149], v[186:189], v[2:5]
	v_mfma_f32_16x16x32_bf16 v[42:45], v[138:141], v[178:181], v[42:45]
	v_mfma_f32_16x16x32_bf16 v[38:41], v[146:149], v[178:181], v[38:41]
	v_mfma_f32_16x16x32_bf16 v[66:69], v[138:141], v[170:173], v[66:69]
	v_mfma_f32_16x16x32_bf16 v[62:65], v[146:149], v[170:173], v[62:65]
	s_setprio 0
	s_barrier
	ds_read_b128 v[190:193], v251 offset:49152
	ds_read_b128 v[194:197], v251 offset:50176
	ds_read_b128 v[182:185], v251 offset:51200
	ds_read_b128 v[186:189], v251 offset:52224
	ds_read_b128 v[174:177], v251 offset:53248
	ds_read_b128 v[178:181], v251 offset:54272
	ds_read_b128 v[166:169], v251 offset:55296
	ds_read_b128 v[170:173], v251 offset:56320
	s_and_b64 vcc, exec, s[10:11]
	s_cbranch_vccnz .LBB0_1632
	s_mov_b32 m0, s91
	v_lshl_add_u64 v[236:237], v[236:237], 0, s[16:17]
	s_add_u32 s10, s68, 0x200080
	global_load_lds_dwordx4 v[236:237], off
	v_lshl_add_u64 v[234:235], v[234:235], 0, s[16:17]
	s_mov_b32 m0, s92
	s_addc_u32 s11, s69, 0
	global_load_lds_dwordx4 v[234:235], off
	v_lshl_add_u64 v[234:235], s[10:11], 0, v[200:201]
	s_mov_b32 m0, s3
	v_lshl_add_u64 v[232:233], v[232:233], 0, s[16:17]
	global_load_lds_dwordx4 v[234:235], off
	v_lshl_add_u64 v[234:235], s[10:11], 0, v[14:15]
	s_mov_b32 m0, s95
	v_lshl_add_u64 v[230:231], v[230:231], 0, s[16:17]
	global_load_lds_dwordx4 v[234:235], off
	s_mov_b32 m0, s93
	s_nop 0
	global_load_lds_dwordx4 v[232:233], off
	s_mov_b32 m0, s94
	s_nop 0
	global_load_lds_dwordx4 v[230:231], off
	s_waitcnt vmcnt(8)
	s_branch .LBB0_1632

.LBB0_1717:
	s_waitcnt lgkmcnt(0)
	s_barrier
	s_setprio 1
	s_waitcnt lgkmcnt(0)
	v_mfma_f32_16x16x32_bf16 v[66:69], v[158:161], v[190:193], v[66:69]
	v_mfma_f32_16x16x32_bf16 v[62:65], v[166:169], v[190:193], v[62:65]
	v_mfma_f32_16x16x32_bf16 v[50:53], v[158:161], v[182:185], v[50:53]
	v_mfma_f32_16x16x32_bf16 v[46:49], v[166:169], v[182:185], v[46:49]
	v_mfma_f32_16x16x32_bf16 v[34:37], v[158:161], v[174:177], v[34:37]
	v_mfma_f32_16x16x32_bf16 v[30:33], v[166:169], v[174:177], v[30:33]
	v_mfma_f32_16x16x32_bf16 v[18:21], v[158:161], v[126:129], v[18:21]
	v_mfma_f32_16x16x32_bf16 v[10:13], v[166:169], v[126:129], v[10:13]
	v_mfma_f32_16x16x32_bf16 v[66:69], v[162:165], v[194:197], v[66:69]
	v_mfma_f32_16x16x32_bf16 v[62:65], v[170:173], v[194:197], v[62:65]
	v_mfma_f32_16x16x32_bf16 v[50:53], v[162:165], v[186:189], v[50:53]
	v_mfma_f32_16x16x32_bf16 v[46:49], v[170:173], v[186:189], v[46:49]
	v_mfma_f32_16x16x32_bf16 v[34:37], v[162:165], v[178:181], v[34:37]
	v_mfma_f32_16x16x32_bf16 v[30:33], v[170:173], v[178:181], v[30:33]
	v_mfma_f32_16x16x32_bf16 v[18:21], v[162:165], v[130:133], v[18:21]
	v_mfma_f32_16x16x32_bf16 v[10:13], v[170:173], v[130:133], v[10:13]
	v_mfma_f32_16x16x32_bf16 v[58:61], v[134:137], v[190:193], v[58:61]
	v_mfma_f32_16x16x32_bf16 v[54:57], v[150:153], v[190:193], v[54:57]
	v_mfma_f32_16x16x32_bf16 v[42:45], v[134:137], v[182:185], v[42:45]
	v_mfma_f32_16x16x32_bf16 v[38:41], v[150:153], v[182:185], v[38:41]
	v_mfma_f32_16x16x32_bf16 v[26:29], v[134:137], v[174:177], v[26:29]
	v_mfma_f32_16x16x32_bf16 v[22:25], v[150:153], v[174:177], v[22:25]
	v_mfma_f32_16x16x32_bf16 v[6:9], v[134:137], v[126:129], v[6:9]
	v_mfma_f32_16x16x32_bf16 v[2:5], v[150:153], v[126:129], v[2:5]
	v_mfma_f32_16x16x32_bf16 v[58:61], v[138:141], v[194:197], v[58:61]
	v_mfma_f32_16x16x32_bf16 v[54:57], v[154:157], v[194:197], v[54:57]
	v_mfma_f32_16x16x32_bf16 v[42:45], v[138:141], v[186:189], v[42:45]
	v_mfma_f32_16x16x32_bf16 v[38:41], v[154:157], v[186:189], v[38:41]
	v_mfma_f32_16x16x32_bf16 v[26:29], v[138:141], v[178:181], v[26:29]
	v_mfma_f32_16x16x32_bf16 v[22:25], v[154:157], v[178:181], v[22:25]
	v_mfma_f32_16x16x32_bf16 v[6:9], v[138:141], v[130:133], v[6:9]
	v_mfma_f32_16x16x32_bf16 v[2:5], v[154:157], v[130:133], v[2:5]
	s_setprio 0
	s_barrier
	s_add_i32 s33, s33, 2
	s_add_u32 s50, s50, 0x100
	s_addc_u32 s51, s51, 0
	s_add_u32 s69, s69, 0x100
	s_addc_u32 s70, s70, 0
	s_cmpk_gt_u32 s33, 0x7d
	s_cbranch_scc1 .LBB0_1728
.LBB0_1718:
	v_add_u32_e32 v126, 0x10000, v226
	ds_read_b128 v[158:161], v126
	ds_read_b128 v[162:165], v126 offset:1024
	ds_read_b128 v[166:169], v126 offset:2048
	ds_read_b128 v[170:173], v126 offset:3072
	v_add_u32_e32 v126, 0x14000, v226
	ds_read_b128 v[134:137], v126
	ds_read_b128 v[138:141], v126 offset:1024
	ds_read_b128 v[150:153], v126 offset:2048
	ds_read_b128 v[154:157], v126 offset:3072
	s_add_u32 s54, s50, 0xffe00080
	s_addc_u32 s55, s51, -1
	s_cmpk_lg_i32 s33, 0x7c
	s_cselect_b64 s[56:57], -1, 0
	s_and_b64 s[52:53], s[56:57], exec
	s_cselect_b32 s53, s70, s13
	s_cselect_b32 s52, s69, s68
	s_cselect_b32 s55, s55, s41
	s_cselect_b32 s54, s54, s67
	v_lshl_add_u64 v[126:127], s[50:51], 0, v[212:213]
	s_add_i32 m0, s1, 0xc000
	ds_read_b128 v[174:177], v227
	ds_read_b128 v[178:181], v227 offset:1024
	ds_read_b128 v[182:185], v227 offset:2048
	ds_read_b128 v[186:189], v227 offset:3072
	ds_read_b128 v[190:193], v227 offset:4096
	ds_read_b128 v[194:197], v227 offset:5120
	ds_read_b128 v[198:201], v227 offset:6144
	ds_read_b128 v[202:205], v227 offset:7168
	global_load_lds_dwordx4 v[126:127], off
	v_lshl_add_u64 v[126:127], s[50:51], 0, v[216:217]
	s_add_i32 m0, s1, 0xe000
	s_nop 0
	global_load_lds_dwordx4 v[126:127], off
	s_waitcnt vmcnt(8)
	s_waitcnt lgkmcnt(0)
	s_barrier
	s_setprio 1
	s_waitcnt lgkmcnt(0)
	v_mfma_f32_16x16x32_bf16 v[126:129], v[158:161], v[174:177], v[146:149]
	v_mfma_f32_16x16x32_bf16 v[130:133], v[166:169], v[174:177], v[142:145]
	v_mfma_f32_16x16x32_bf16 v[114:117], v[158:161], v[182:185], v[114:117]
	v_mfma_f32_16x16x32_bf16 v[110:113], v[166:169], v[182:185], v[110:113]
	v_mfma_f32_16x16x32_bf16 v[98:101], v[158:161], v[190:193], v[98:101]
	v_mfma_f32_16x16x32_bf16 v[94:97], v[166:169], v[190:193], v[94:97]
	v_mfma_f32_16x16x32_bf16 v[82:85], v[158:161], v[198:201], v[82:85]
	v_mfma_f32_16x16x32_bf16 v[78:81], v[166:169], v[198:201], v[78:81]
	v_mfma_f32_16x16x32_bf16 v[126:129], v[162:165], v[178:181], v[126:129]
	v_mfma_f32_16x16x32_bf16 v[130:133], v[170:173], v[178:181], v[130:133]
	v_mfma_f32_16x16x32_bf16 v[114:117], v[162:165], v[186:189], v[114:117]
	v_mfma_f32_16x16x32_bf16 v[110:113], v[170:173], v[186:189], v[110:113]
	v_mfma_f32_16x16x32_bf16 v[98:101], v[162:165], v[194:197], v[98:101]
	v_mfma_f32_16x16x32_bf16 v[94:97], v[170:173], v[194:197], v[94:97]
	v_mfma_f32_16x16x32_bf16 v[82:85], v[162:165], v[202:205], v[82:85]
	v_mfma_f32_16x16x32_bf16 v[78:81], v[170:173], v[202:205], v[78:81]
	v_mfma_f32_16x16x32_bf16 v[122:125], v[134:137], v[174:177], v[122:125]
	v_mfma_f32_16x16x32_bf16 v[118:121], v[150:153], v[174:177], v[118:121]
	v_mfma_f32_16x16x32_bf16 v[106:109], v[134:137], v[182:185], v[106:109]
	v_mfma_f32_16x16x32_bf16 v[102:105], v[150:153], v[182:185], v[102:105]
	v_mfma_f32_16x16x32_bf16 v[90:93], v[134:137], v[190:193], v[90:93]
	v_mfma_f32_16x16x32_bf16 v[86:89], v[150:153], v[190:193], v[86:89]
	v_mfma_f32_16x16x32_bf16 v[74:77], v[134:137], v[198:201], v[74:77]
	v_mfma_f32_16x16x32_bf16 v[70:73], v[150:153], v[198:201], v[70:73]
	v_mfma_f32_16x16x32_bf16 v[122:125], v[138:141], v[178:181], v[122:125]
	v_mfma_f32_16x16x32_bf16 v[118:121], v[154:157], v[178:181], v[118:121]
	v_mfma_f32_16x16x32_bf16 v[106:109], v[138:141], v[186:189], v[106:109]
	v_mfma_f32_16x16x32_bf16 v[102:105], v[154:157], v[186:189], v[102:105]
	v_mfma_f32_16x16x32_bf16 v[90:93], v[138:141], v[194:197], v[90:93]
	v_mfma_f32_16x16x32_bf16 v[86:89], v[154:157], v[194:197], v[86:89]
	v_mfma_f32_16x16x32_bf16 v[74:77], v[138:141], v[202:205], v[74:77]
	v_mfma_f32_16x16x32_bf16 v[70:73], v[154:157], v[202:205], v[70:73]
	s_setprio 0
	s_barrier
	ds_read_b128 v[190:193], v227 offset:16384
	ds_read_b128 v[194:197], v227 offset:17408
	ds_read_b128 v[182:185], v227 offset:18432
	ds_read_b128 v[186:189], v227 offset:19456
	ds_read_b128 v[174:177], v227 offset:20480
	ds_read_b128 v[178:181], v227 offset:21504
	ds_read_b128 v[142:145], v227 offset:22528
	ds_read_b128 v[146:149], v227 offset:23552
	s_or_b64 s[56:57], s[42:43], s[56:57]
	s_xor_b64 s[58:59], s[56:57], -1
	s_mov_b64 s[60:61], -1
	s_and_b64 vcc, exec, s[58:59]
	s_cbranch_vccz .LBB0_1720
	s_waitcnt vmcnt(2)
	s_mov_b64 s[60:61], 0

.LBB0_1722:
	s_waitcnt lgkmcnt(0)
	s_barrier
	s_setprio 1
	s_waitcnt lgkmcnt(0)
	v_mfma_f32_16x16x32_bf16 v[66:69], v[158:161], v[190:193], v[66:69]
	v_mfma_f32_16x16x32_bf16 v[62:65], v[166:169], v[190:193], v[62:65]
	v_mfma_f32_16x16x32_bf16 v[50:53], v[158:161], v[182:185], v[50:53]
	v_mfma_f32_16x16x32_bf16 v[46:49], v[166:169], v[182:185], v[46:49]
	v_mfma_f32_16x16x32_bf16 v[34:37], v[158:161], v[174:177], v[34:37]
	v_mfma_f32_16x16x32_bf16 v[30:33], v[166:169], v[174:177], v[30:33]
	v_mfma_f32_16x16x32_bf16 v[18:21], v[158:161], v[142:145], v[18:21]
	v_mfma_f32_16x16x32_bf16 v[10:13], v[166:169], v[142:145], v[10:13]
	v_mfma_f32_16x16x32_bf16 v[66:69], v[162:165], v[194:197], v[66:69]
	v_mfma_f32_16x16x32_bf16 v[62:65], v[170:173], v[194:197], v[62:65]
	v_mfma_f32_16x16x32_bf16 v[50:53], v[162:165], v[186:189], v[50:53]
	v_mfma_f32_16x16x32_bf16 v[46:49], v[170:173], v[186:189], v[46:49]
	v_mfma_f32_16x16x32_bf16 v[34:37], v[162:165], v[178:181], v[34:37]
	v_mfma_f32_16x16x32_bf16 v[30:33], v[170:173], v[178:181], v[30:33]
	v_mfma_f32_16x16x32_bf16 v[18:21], v[162:165], v[146:149], v[18:21]
	v_mfma_f32_16x16x32_bf16 v[10:13], v[170:173], v[146:149], v[10:13]
	v_mfma_f32_16x16x32_bf16 v[58:61], v[134:137], v[190:193], v[58:61]
	v_mfma_f32_16x16x32_bf16 v[54:57], v[150:153], v[190:193], v[54:57]
	v_mfma_f32_16x16x32_bf16 v[42:45], v[134:137], v[182:185], v[42:45]
	v_mfma_f32_16x16x32_bf16 v[38:41], v[150:153], v[182:185], v[38:41]
	v_mfma_f32_16x16x32_bf16 v[26:29], v[134:137], v[174:177], v[26:29]
	v_mfma_f32_16x16x32_bf16 v[22:25], v[150:153], v[174:177], v[22:25]
	v_mfma_f32_16x16x32_bf16 v[6:9], v[134:137], v[142:145], v[6:9]
	v_mfma_f32_16x16x32_bf16 v[2:5], v[150:153], v[142:145], v[2:5]
	v_mfma_f32_16x16x32_bf16 v[58:61], v[138:141], v[194:197], v[58:61]
	v_mfma_f32_16x16x32_bf16 v[54:57], v[154:157], v[194:197], v[54:57]
	v_mfma_f32_16x16x32_bf16 v[42:45], v[138:141], v[186:189], v[42:45]
	v_mfma_f32_16x16x32_bf16 v[38:41], v[154:157], v[186:189], v[38:41]
	v_mfma_f32_16x16x32_bf16 v[26:29], v[138:141], v[178:181], v[26:29]
	v_mfma_f32_16x16x32_bf16 v[22:25], v[154:157], v[178:181], v[22:25]
	v_mfma_f32_16x16x32_bf16 v[6:9], v[138:141], v[146:149], v[6:9]
	v_mfma_f32_16x16x32_bf16 v[2:5], v[154:157], v[146:149], v[2:5]
	s_setprio 0
	s_barrier
	v_add_u32_e32 v134, 0x18000, v226
	v_add_u32_e32 v142, 0x1c000, v226
	ds_read_b128 v[158:161], v134
	ds_read_b128 v[162:165], v134 offset:1024
	ds_read_b128 v[166:169], v134 offset:2048
	ds_read_b128 v[170:173], v134 offset:3072
	ds_read_b128 v[134:137], v142
	ds_read_b128 v[138:141], v142 offset:1024
	ds_read_b128 v[150:153], v142 offset:2048
	ds_read_b128 v[154:157], v142 offset:3072
	ds_read_b128 v[198:201], v227 offset:32768
	ds_read_b128 v[202:205], v227 offset:33792
	ds_read_b128 v[190:193], v227 offset:34816
	ds_read_b128 v[194:197], v227 offset:35840
	ds_read_b128 v[182:185], v227 offset:36864
	ds_read_b128 v[186:189], v227 offset:37888
	ds_read_b128 v[174:177], v227 offset:38912
	ds_read_b128 v[178:181], v227 offset:39936
	s_mov_b64 s[60:61], -1
	s_and_b64 vcc, exec, s[58:59]
	s_cbranch_vccz .LBB0_1724
	s_waitcnt vmcnt(0)
	s_mov_b64 s[60:61], 0

.LBB0_1726:
	s_waitcnt lgkmcnt(0)
	s_barrier
	s_setprio 1
	s_waitcnt lgkmcnt(0)
	v_mfma_f32_16x16x32_bf16 v[126:129], v[158:161], v[198:201], v[126:129]
	v_mfma_f32_16x16x32_bf16 v[146:149], v[162:165], v[202:205], v[126:129]
	v_mfma_f32_16x16x32_bf16 v[126:129], v[166:169], v[198:201], v[130:133]
	v_mfma_f32_16x16x32_bf16 v[114:117], v[158:161], v[190:193], v[114:117]
	v_mfma_f32_16x16x32_bf16 v[110:113], v[166:169], v[190:193], v[110:113]
	v_mfma_f32_16x16x32_bf16 v[98:101], v[158:161], v[182:185], v[98:101]
	v_mfma_f32_16x16x32_bf16 v[94:97], v[166:169], v[182:185], v[94:97]
	v_mfma_f32_16x16x32_bf16 v[82:85], v[158:161], v[174:177], v[82:85]
	v_mfma_f32_16x16x32_bf16 v[78:81], v[166:169], v[174:177], v[78:81]
	v_mfma_f32_16x16x32_bf16 v[142:145], v[170:173], v[202:205], v[126:129]
	v_mfma_f32_16x16x32_bf16 v[114:117], v[162:165], v[194:197], v[114:117]
	v_mfma_f32_16x16x32_bf16 v[110:113], v[170:173], v[194:197], v[110:113]
	v_mfma_f32_16x16x32_bf16 v[98:101], v[162:165], v[186:189], v[98:101]
	v_mfma_f32_16x16x32_bf16 v[94:97], v[170:173], v[186:189], v[94:97]
	v_mfma_f32_16x16x32_bf16 v[82:85], v[162:165], v[178:181], v[82:85]
	v_mfma_f32_16x16x32_bf16 v[78:81], v[170:173], v[178:181], v[78:81]
	v_mfma_f32_16x16x32_bf16 v[122:125], v[134:137], v[198:201], v[122:125]
	v_mfma_f32_16x16x32_bf16 v[118:121], v[150:153], v[198:201], v[118:121]
	v_mfma_f32_16x16x32_bf16 v[106:109], v[134:137], v[190:193], v[106:109]
	v_mfma_f32_16x16x32_bf16 v[102:105], v[150:153], v[190:193], v[102:105]
	v_mfma_f32_16x16x32_bf16 v[90:93], v[134:137], v[182:185], v[90:93]
	v_mfma_f32_16x16x32_bf16 v[86:89], v[150:153], v[182:185], v[86:89]
	v_mfma_f32_16x16x32_bf16 v[74:77], v[134:137], v[174:177], v[74:77]
	v_mfma_f32_16x16x32_bf16 v[70:73], v[150:153], v[174:177], v[70:73]
	v_mfma_f32_16x16x32_bf16 v[122:125], v[138:141], v[202:205], v[122:125]
	v_mfma_f32_16x16x32_bf16 v[118:121], v[154:157], v[202:205], v[118:121]
	v_mfma_f32_16x16x32_bf16 v[106:109], v[138:141], v[194:197], v[106:109]
	v_mfma_f32_16x16x32_bf16 v[102:105], v[154:157], v[194:197], v[102:105]
	v_mfma_f32_16x16x32_bf16 v[90:93], v[138:141], v[186:189], v[90:93]
	v_mfma_f32_16x16x32_bf16 v[86:89], v[154:157], v[186:189], v[86:89]
	v_mfma_f32_16x16x32_bf16 v[74:77], v[138:141], v[178:181], v[74:77]
	v_mfma_f32_16x16x32_bf16 v[70:73], v[154:157], v[178:181], v[70:73]
	s_setprio 0
	s_barrier
	ds_read_b128 v[190:193], v227 offset:49152
	ds_read_b128 v[194:197], v227 offset:50176
	ds_read_b128 v[182:185], v227 offset:51200
	ds_read_b128 v[186:189], v227 offset:52224
	ds_read_b128 v[174:177], v227 offset:53248
	ds_read_b128 v[178:181], v227 offset:54272
	ds_read_b128 v[126:129], v227 offset:55296
	ds_read_b128 v[130:133], v227 offset:56320
	s_andn2_b64 vcc, exec, s[56:57]
	s_cbranch_vccnz .LBB0_1717
	s_mov_b32 m0, s29
	v_lshl_add_u64 v[198:199], v[224:225], 0, s[16:17]
	s_add_u32 s52, s52, 0x200080
	global_load_lds_dwordx4 v[198:199], off
	v_lshl_add_u64 v[198:199], v[222:223], 0, s[16:17]
	s_mov_b32 m0, s36
	s_addc_u32 s53, s53, 0
	global_load_lds_dwordx4 v[198:199], off
	v_lshl_add_u64 v[198:199], s[52:53], 0, v[206:207]
	s_mov_b32 m0, s62
	s_nop 0
	global_load_lds_dwordx4 v[198:199], off
	v_lshl_add_u64 v[198:199], s[52:53], 0, v[210:211]
	s_mov_b32 m0, s63
	s_nop 0
	global_load_lds_dwordx4 v[198:199], off
	v_lshl_add_u64 v[198:199], v[220:221], 0, s[16:17]
	s_mov_b32 m0, s38
	s_nop 0
	global_load_lds_dwordx4 v[198:199], off
	v_lshl_add_u64 v[198:199], v[218:219], 0, s[16:17]
	s_mov_b32 m0, s49
	s_nop 0
	global_load_lds_dwordx4 v[198:199], off
	s_waitcnt vmcnt(8)
	s_branch .LBB0_1717
